# sc1 write-through on dwordx4 epilogue stores of P2/P3/P4/P7 (less dirty L2 at the seams)
# speedup vs baseline: 1.0090x; 1.0090x over previous
; #define PG8_STAGE(bufoff, gbase, voff) do { _Pragma("unroll") for (int _i = 0; _i < 2; ++_i) \
;         __builtin_amdgcn_global_load_lds((const unsigned*)((const char*)(gbase) + (voff)[_i]), (LAS unsigned*)(lds + (bufoff) + ldsw + _i * 8192), 16, 0, 0); } while (0)
; #define PG8_LDA(dst, b, h) do { _Pragma("unroll") for (int m = 0; m < 4; ++m) _Pragma("unroll") for (int k = 0; k < 2; ++k) dst[m][k] = *(const LAS bf16x8*)(lds + PG8_SA(b, h) + aoff + m * 2048 + k * 1024); } while (0)
; #define PG8_LDB(dst, b, h) do { _Pragma("unroll") for (int n = 0; n < 2; ++n) _Pragma("unroll") for (int k = 0; k < 2; ++k) dst[n][k] = *(const LAS bf16x8*)(lds + PG8_SB(b, h) + boff + n * 2048 + k * 1024); } while (0)
; #define PG8_MMA(ai, bj, At, Bt) do { __builtin_amdgcn_s_setprio(1); _Pragma("unroll") for (int m = 0; m < 4; ++m) _Pragma("unroll") for (int n = 0; n < 2; ++n) _Pragma("unroll") for (int k = 0; k < 2; ++k) \
;         acc[ai][bj][m][n] = __builtin_amdgcn_mfma_f32_16x16x32_bf16(Bt[n][k], At[m][k], acc[ai][bj][m][n], 0, 0, 0); __builtin_amdgcn_s_setprio(0); } while (0)
; #define PG8_WAIT_V(n) asm volatile("s_waitcnt vmcnt(" #n ")" ::: "memory")
; #define PG8_WAIT_L(n) asm volatile("s_waitcnt lgkmcnt(" #n ")" ::: "memory")
; template <class Epi, class Sched>
; __device__ __forceinline__ void gemm_phase(LAS unsigned char* lds, const int K, const Sched& S, const Epi& E) {
;     ...
;         for (int t = 0; t < nt; t += 2) {
;             const bool last = (t == nt - 2);
;             const char* a1 = cA + (size_t)(t + 1) * kstep;
;             const char* a2 = last ? nA : cA + (size_t)(t + 2) * kstep; const char* b2 = last ? nB : cB + (size_t)(t + 2) * kstep;
;             const char* a3 = a2 + kstep; const char* b3 = b2 + kstep;
;             PG8_LDB(B0, 0, 0); PG8_SCHED; PG8_LDA(At, 0, 0); PG8_STAGE(PG8_SA(1, 1), a1 + hstepA, voffA);
;             PG8_WAIT_L(8); PG8_BAR; PG8_WAIT_L(0); PG8_MMA(0, 0, At, B0); PG8_BAR; PG8_SCHED;
;             PG8_LDB(B1, 0, 1); PG8_STAGE(PG8_SB(0, 0), b2, voffB);
;             PG8_BAR; PG8_WAIT_L(0); PG8_MMA(0, 1, At, B1); PG8_BAR;
;             PG8_LDA(At, 0, 1); PG8_STAGE(PG8_SA(0, 0), a2, voffA);
;             PG8_BAR; PG8_WAIT_L(0); PG8_MMA(1, 0, At, B0); PG8_BAR; PG8_SCHED;
;             PG8_STAGE(PG8_SB(0, 1), b2 + hstep, voffB);
;             PG8_WAIT_V(6); PG8_BAR; PG8_MMA(1, 1, At, B1); PG8_BAR;
.LBB0_189:
	ds_read_b128 v[164:167], v160
	ds_read_b128 v[174:177], v160 offset:1024
	ds_read_b128 v[178:181], v160 offset:2048
	ds_read_b128 v[182:185], v160 offset:3072
	s_add_u32 s72, s70, 0xfffc0080
	s_addc_u32 s73, s71, -1
	s_cmp_eq_u32 s67, 12
	s_cselect_b32 s75, s45, s73
	s_cselect_b32 s74, s44, s72
	s_cselect_b32 s73, s47, s65
	s_cselect_b32 s72, s46, s43
	v_lshl_add_u64 v[168:169], s[70:71], 0, v[156:157]
	s_add_i32 m0, s55, 0xc000
	ds_read_b128 v[186:189], v161
	ds_read_b128 v[190:193], v161 offset:1024
	ds_read_b128 v[194:197], v161 offset:2048
	ds_read_b128 v[198:201], v161 offset:3072
	ds_read_b128 v[202:205], v161 offset:4096
	ds_read_b128 v[206:209], v161 offset:5120
	ds_read_b128 v[210:213], v161 offset:6144
	ds_read_b128 v[214:217], v161 offset:7168
	global_load_lds_dwordx4 v[168:169], off
	v_lshl_add_u64 v[168:169], s[70:71], 0, v[158:159]
	s_add_i32 m0, s55, 0xe000
	s_nop 0
	global_load_lds_dwordx4 v[168:169], off
	s_waitcnt lgkmcnt(8)
	s_barrier
	s_waitcnt lgkmcnt(0)
	s_setprio 1
	s_waitcnt lgkmcnt(0)
	v_mfma_f32_16x16x32_bf16 v[124:127], v[164:167], v[186:189], v[124:127]
	v_mfma_f32_16x16x32_bf16 v[120:123], v[178:181], v[186:189], v[120:123]
	v_mfma_f32_16x16x32_bf16 v[112:115], v[164:167], v[194:197], v[112:115]
	v_mfma_f32_16x16x32_bf16 v[104:107], v[178:181], v[194:197], v[104:107]
	v_mfma_f32_16x16x32_bf16 v[100:103], v[164:167], v[202:205], v[100:103]
	v_mfma_f32_16x16x32_bf16 v[92:95], v[178:181], v[202:205], v[92:95]
	v_mfma_f32_16x16x32_bf16 v[84:87], v[164:167], v[210:213], v[84:87]
	v_mfma_f32_16x16x32_bf16 v[76:79], v[178:181], v[210:213], v[76:79]
	v_mfma_f32_16x16x32_bf16 v[124:127], v[174:177], v[190:193], v[124:127]
	v_mfma_f32_16x16x32_bf16 v[120:123], v[182:185], v[190:193], v[120:123]
	v_mfma_f32_16x16x32_bf16 v[112:115], v[174:177], v[198:201], v[112:115]
	v_mfma_f32_16x16x32_bf16 v[104:107], v[182:185], v[198:201], v[104:107]
	v_mfma_f32_16x16x32_bf16 v[100:103], v[174:177], v[206:209], v[100:103]
	v_mfma_f32_16x16x32_bf16 v[92:95], v[182:185], v[206:209], v[92:95]
	v_mfma_f32_16x16x32_bf16 v[84:87], v[174:177], v[214:217], v[84:87]
	v_mfma_f32_16x16x32_bf16 v[76:79], v[182:185], v[214:217], v[76:79]
	s_setprio 0
	s_barrier
	s_add_i32 vcc_lo, s33, s54
	v_lshl_add_u64 v[168:169], s[72:73], 0, v[130:131]
	s_mov_b32 m0, vcc_lo
	ds_read_b128 v[218:221], v162
	ds_read_b128 v[222:225], v162 offset:1024
	ds_read_b128 v[226:229], v162 offset:2048
	ds_read_b128 v[230:233], v162 offset:3072
	global_load_lds_dwordx4 v[168:169], off
	v_lshl_add_u64 v[234:235], s[72:73], 0, v[134:135]
	s_add_i32 m0, vcc_lo, 0x2000
	s_nop 0
	global_load_lds_dwordx4 v[234:235], off
	s_barrier
	s_waitcnt lgkmcnt(0)
	s_setprio 1
	s_waitcnt lgkmcnt(0)
	v_mfma_f32_16x16x32_bf16 v[116:119], v[218:221], v[186:189], v[116:119]
	v_mfma_f32_16x16x32_bf16 v[108:111], v[226:229], v[186:189], v[108:111]
	v_mfma_f32_16x16x32_bf16 v[96:99], v[218:221], v[194:197], v[96:99]
	v_mfma_f32_16x16x32_bf16 v[88:91], v[226:229], v[194:197], v[88:91]
	v_mfma_f32_16x16x32_bf16 v[80:83], v[218:221], v[202:205], v[80:83]
	v_mfma_f32_16x16x32_bf16 v[72:75], v[226:229], v[202:205], v[72:75]
	v_mfma_f32_16x16x32_bf16 v[68:71], v[218:221], v[210:213], v[68:71]
	v_mfma_f32_16x16x32_bf16 v[64:67], v[226:229], v[210:213], v[64:67]
	v_mfma_f32_16x16x32_bf16 v[116:119], v[222:225], v[190:193], v[116:119]
	v_mfma_f32_16x16x32_bf16 v[108:111], v[230:233], v[190:193], v[108:111]
	v_mfma_f32_16x16x32_bf16 v[96:99], v[222:225], v[198:201], v[96:99]
	v_mfma_f32_16x16x32_bf16 v[88:91], v[230:233], v[198:201], v[88:91]
	v_mfma_f32_16x16x32_bf16 v[80:83], v[222:225], v[206:209], v[80:83]
	v_mfma_f32_16x16x32_bf16 v[72:75], v[230:233], v[206:209], v[72:75]
	v_mfma_f32_16x16x32_bf16 v[68:71], v[222:225], v[214:217], v[68:71]
	v_mfma_f32_16x16x32_bf16 v[64:67], v[230:233], v[214:217], v[64:67]
	s_setprio 0
	s_mov_b32 m0, s55
	v_lshl_add_u64 v[236:237], s[74:75], 0, v[128:129]
	s_barrier
	ds_read_b128 v[186:189], v161 offset:16384
	ds_read_b128 v[190:193], v161 offset:17408
	ds_read_b128 v[194:197], v161 offset:18432
	ds_read_b128 v[198:201], v161 offset:19456
	ds_read_b128 v[202:205], v161 offset:20480
	ds_read_b128 v[206:209], v161 offset:21504
	ds_read_b128 v[210:213], v161 offset:22528
	ds_read_b128 v[214:217], v161 offset:23552
	global_load_lds_dwordx4 v[236:237], off
	v_lshl_add_u64 v[238:239], s[74:75], 0, v[132:133]
	s_mov_b32 m0, s86
	s_nop 0
	global_load_lds_dwordx4 v[238:239], off
	s_barrier
	s_waitcnt lgkmcnt(0)
	s_setprio 1
	s_waitcnt lgkmcnt(0)
	v_mfma_f32_16x16x32_bf16 v[60:63], v[164:167], v[186:189], v[60:63]
	v_mfma_f32_16x16x32_bf16 v[56:59], v[178:181], v[186:189], v[56:59]
	v_mfma_f32_16x16x32_bf16 v[52:55], v[164:167], v[194:197], v[52:55]
	v_mfma_f32_16x16x32_bf16 v[44:47], v[178:181], v[194:197], v[44:47]
	v_mfma_f32_16x16x32_bf16 v[36:39], v[164:167], v[202:205], v[36:39]
	v_mfma_f32_16x16x32_bf16 v[28:31], v[178:181], v[202:205], v[28:31]
	v_mfma_f32_16x16x32_bf16 v[20:23], v[164:167], v[210:213], v[20:23]
	v_mfma_f32_16x16x32_bf16 v[12:15], v[178:181], v[210:213], v[12:15]
	v_mfma_f32_16x16x32_bf16 v[60:63], v[174:177], v[190:193], v[60:63]
	v_mfma_f32_16x16x32_bf16 v[56:59], v[182:185], v[190:193], v[56:59]
	v_mfma_f32_16x16x32_bf16 v[52:55], v[174:177], v[198:201], v[52:55]
	v_mfma_f32_16x16x32_bf16 v[44:47], v[182:185], v[198:201], v[44:47]
	v_mfma_f32_16x16x32_bf16 v[36:39], v[174:177], v[206:209], v[36:39]
	v_mfma_f32_16x16x32_bf16 v[28:31], v[182:185], v[206:209], v[28:31]
	v_mfma_f32_16x16x32_bf16 v[20:23], v[174:177], v[214:217], v[20:23]
	v_mfma_f32_16x16x32_bf16 v[12:15], v[182:185], v[214:217], v[12:15]
	s_setprio 0
	s_barrier
; #define PG8_STAGE(bufoff, gbase, voff) do { _Pragma("unroll") for (int _i = 0; _i < 2; ++_i) \
;         __builtin_amdgcn_global_load_lds((const unsigned*)((const char*)(gbase) + (voff)[_i]), (LAS unsigned*)(lds + (bufoff) + ldsw + _i * 8192), 16, 0, 0); } while (0)
; #define PG8_LDA(dst, b, h) do { _Pragma("unroll") for (int m = 0; m < 4; ++m) _Pragma("unroll") for (int k = 0; k < 2; ++k) dst[m][k] = *(const LAS bf16x8*)(lds + PG8_SA(b, h) + aoff + m * 2048 + k * 1024); } while (0)
; #define PG8_LDB(dst, b, h) do { _Pragma("unroll") for (int n = 0; n < 2; ++n) _Pragma("unroll") for (int k = 0; k < 2; ++k) dst[n][k] = *(const LAS bf16x8*)(lds + PG8_SB(b, h) + boff + n * 2048 + k * 1024); } while (0)
; #define PG8_MMA(ai, bj, At, Bt) do { __builtin_amdgcn_s_setprio(1); _Pragma("unroll") for (int m = 0; m < 4; ++m) _Pragma("unroll") for (int n = 0; n < 2; ++n) _Pragma("unroll") for (int k = 0; k < 2; ++k) \
;         acc[ai][bj][m][n] = __builtin_amdgcn_mfma_f32_16x16x32_bf16(Bt[n][k], At[m][k], acc[ai][bj][m][n], 0, 0, 0); __builtin_amdgcn_s_setprio(0); } while (0)
; #define PG8_WAIT_V(n) asm volatile("s_waitcnt vmcnt(" #n ")" ::: "memory")
; #define PG8_WAIT_L(n) asm volatile("s_waitcnt lgkmcnt(" #n ")" ::: "memory")
; #define PG8_BAR __builtin_amdgcn_s_barrier()
; #define PG8_SCHED __builtin_amdgcn_sched_barrier(0)
; template <class Epi, class Sched>
; __device__ __forceinline__ void gemm_phase(LAS unsigned char* lds, const int K, const Sched& S, const Epi& E) {
;     ...
;             PG8_STAGE(PG8_SB(0, 1), b2 + hstep, voffB);
;             PG8_WAIT_V(6); PG8_BAR; PG8_MMA(1, 1, At, B1); PG8_BAR;
;             PG8_LDB(B0, 1, 0); PG8_SCHED; PG8_LDA(At, 1, 0); PG8_STAGE(PG8_SA(0, 1), a2 + hstepA, voffA);
;             PG8_WAIT_L(8); PG8_BAR; PG8_WAIT_L(0); PG8_MMA(0, 0, At, B0); PG8_BAR; PG8_SCHED;
;             PG8_LDB(B1, 1, 1); PG8_STAGE(PG8_SB(1, 0), b3, voffB);
;             PG8_BAR; PG8_WAIT_L(0); PG8_MMA(0, 1, At, B1); PG8_BAR;
;             PG8_LDA(At, 1, 1); PG8_STAGE(PG8_SA(1, 0), a3, voffA);
;             PG8_BAR; PG8_WAIT_L(0); PG8_MMA(1, 0, At, B0); PG8_BAR; PG8_SCHED;
	s_add_u32 vcc_lo, s72, 0x40000
	s_addc_u32 vcc_hi, s73, 0
	s_add_i32 s79, s52, s54
	v_lshl_add_u64 v[164:165], vcc, 0, v[130:131]
	s_mov_b32 m0, s79
	s_nop 0
	global_load_lds_dwordx4 v[164:165], off
	v_lshl_add_u64 v[164:165], vcc, 0, v[134:135]
	s_add_i32 m0, s79, 0x2000
	s_nop 0
	global_load_lds_dwordx4 v[164:165], off
	s_waitcnt vmcnt(6)
	s_barrier
	s_setprio 1
	v_mfma_f32_16x16x32_bf16 v[48:51], v[218:221], v[186:189], v[48:51]
	v_mfma_f32_16x16x32_bf16 v[40:43], v[226:229], v[186:189], v[40:43]
	v_mfma_f32_16x16x32_bf16 v[32:35], v[218:221], v[194:197], v[32:35]
	v_mfma_f32_16x16x32_bf16 v[24:27], v[226:229], v[194:197], v[24:27]
	v_mfma_f32_16x16x32_bf16 v[16:19], v[218:221], v[202:205], v[16:19]
	v_mfma_f32_16x16x32_bf16 v[8:11], v[226:229], v[202:205], v[8:11]
	v_mfma_f32_16x16x32_bf16 v[4:7], v[218:221], v[210:213], v[4:7]
	v_mfma_f32_16x16x32_bf16 v[0:3], v[226:229], v[210:213], v[0:3]
	v_mfma_f32_16x16x32_bf16 v[48:51], v[222:225], v[190:193], v[48:51]
	v_mfma_f32_16x16x32_bf16 v[40:43], v[230:233], v[190:193], v[40:43]
	v_mfma_f32_16x16x32_bf16 v[32:35], v[222:225], v[198:201], v[32:35]
	v_mfma_f32_16x16x32_bf16 v[24:27], v[230:233], v[198:201], v[24:27]
	v_mfma_f32_16x16x32_bf16 v[16:19], v[222:225], v[206:209], v[16:19]
	v_mfma_f32_16x16x32_bf16 v[8:11], v[230:233], v[206:209], v[8:11]
	v_mfma_f32_16x16x32_bf16 v[4:7], v[222:225], v[214:217], v[4:7]
	v_mfma_f32_16x16x32_bf16 v[0:3], v[230:233], v[214:217], v[0:3]
	s_setprio 0
	s_add_i32 s79, 0, 0x18000
	v_add_u32_e32 v173, s79, v139
	s_barrier
	ds_read_b128 v[164:167], v173
	ds_read_b128 v[174:177], v173 offset:1024
	ds_read_b128 v[178:181], v173 offset:2048
	ds_read_b128 v[182:185], v173 offset:3072
	s_add_u32 s74, s74, 0x40000
	s_addc_u32 s75, s75, 0
	s_mov_b32 m0, s56
	v_lshl_add_u64 v[218:219], s[74:75], 0, v[128:129]
	ds_read_b128 v[186:189], v161 offset:32768
	ds_read_b128 v[190:193], v161 offset:33792
	ds_read_b128 v[194:197], v161 offset:34816
	ds_read_b128 v[198:201], v161 offset:35840
	ds_read_b128 v[202:205], v161 offset:36864
	ds_read_b128 v[206:209], v161 offset:37888
	ds_read_b128 v[210:213], v161 offset:38912
	ds_read_b128 v[214:217], v161 offset:39936
	global_load_lds_dwordx4 v[218:219], off
	v_lshl_add_u64 v[218:219], s[74:75], 0, v[132:133]
	s_mov_b32 m0, s57
	s_nop 0
	global_load_lds_dwordx4 v[218:219], off
	s_waitcnt lgkmcnt(8)
	s_barrier
	s_waitcnt lgkmcnt(0)
	s_setprio 1
	s_waitcnt lgkmcnt(0)
	v_mfma_f32_16x16x32_bf16 v[124:127], v[164:167], v[186:189], v[124:127]
	v_mfma_f32_16x16x32_bf16 v[120:123], v[178:181], v[186:189], v[120:123]
	v_mfma_f32_16x16x32_bf16 v[112:115], v[164:167], v[194:197], v[112:115]
	v_mfma_f32_16x16x32_bf16 v[104:107], v[178:181], v[194:197], v[104:107]
	v_mfma_f32_16x16x32_bf16 v[100:103], v[164:167], v[202:205], v[100:103]
	v_mfma_f32_16x16x32_bf16 v[92:95], v[178:181], v[202:205], v[92:95]
	v_mfma_f32_16x16x32_bf16 v[84:87], v[164:167], v[210:213], v[84:87]
	v_mfma_f32_16x16x32_bf16 v[76:79], v[178:181], v[210:213], v[76:79]
	v_mfma_f32_16x16x32_bf16 v[124:127], v[174:177], v[190:193], v[124:127]
	v_mfma_f32_16x16x32_bf16 v[120:123], v[182:185], v[190:193], v[120:123]
	v_mfma_f32_16x16x32_bf16 v[112:115], v[174:177], v[198:201], v[112:115]
	v_mfma_f32_16x16x32_bf16 v[104:107], v[182:185], v[198:201], v[104:107]
	v_mfma_f32_16x16x32_bf16 v[100:103], v[174:177], v[206:209], v[100:103]
	v_mfma_f32_16x16x32_bf16 v[92:95], v[182:185], v[206:209], v[92:95]
	v_mfma_f32_16x16x32_bf16 v[84:87], v[174:177], v[214:217], v[84:87]
	v_mfma_f32_16x16x32_bf16 v[76:79], v[182:185], v[214:217], v[76:79]
	s_setprio 0
	s_barrier
	s_add_i32 s74, 0, 0x1c000
	s_add_i32 s75, s79, s54
	v_add_u32_e32 v173, s74, v139
	v_lshl_add_u64 v[168:169], v[168:169], 0, s[38:39]
	s_mov_b32 m0, s75
	ds_read_b128 v[218:221], v173
	ds_read_b128 v[222:225], v173 offset:1024
	ds_read_b128 v[226:229], v173 offset:2048
	ds_read_b128 v[230:233], v173 offset:3072
	global_load_lds_dwordx4 v[168:169], off
	v_lshl_add_u64 v[168:169], v[234:235], 0, s[38:39]
	s_add_i32 m0, s75, 0x2000
	s_nop 0
	global_load_lds_dwordx4 v[168:169], off
	s_barrier
	s_waitcnt lgkmcnt(0)
	s_setprio 1
	s_waitcnt lgkmcnt(0)
	v_mfma_f32_16x16x32_bf16 v[116:119], v[218:221], v[186:189], v[116:119]
	v_mfma_f32_16x16x32_bf16 v[108:111], v[226:229], v[186:189], v[108:111]
	v_mfma_f32_16x16x32_bf16 v[96:99], v[218:221], v[194:197], v[96:99]
	v_mfma_f32_16x16x32_bf16 v[88:91], v[226:229], v[194:197], v[88:91]
	v_mfma_f32_16x16x32_bf16 v[80:83], v[218:221], v[202:205], v[80:83]
	v_mfma_f32_16x16x32_bf16 v[72:75], v[226:229], v[202:205], v[72:75]
	v_mfma_f32_16x16x32_bf16 v[68:71], v[218:221], v[210:213], v[68:71]
	v_mfma_f32_16x16x32_bf16 v[64:67], v[226:229], v[210:213], v[64:67]
	v_mfma_f32_16x16x32_bf16 v[116:119], v[222:225], v[190:193], v[116:119]
	v_mfma_f32_16x16x32_bf16 v[108:111], v[230:233], v[190:193], v[108:111]
	v_mfma_f32_16x16x32_bf16 v[96:99], v[222:225], v[198:201], v[96:99]
	v_mfma_f32_16x16x32_bf16 v[88:91], v[230:233], v[198:201], v[88:91]
	v_mfma_f32_16x16x32_bf16 v[80:83], v[222:225], v[206:209], v[80:83]
	v_mfma_f32_16x16x32_bf16 v[72:75], v[230:233], v[206:209], v[72:75]
	v_mfma_f32_16x16x32_bf16 v[68:71], v[222:225], v[214:217], v[68:71]
	v_mfma_f32_16x16x32_bf16 v[64:67], v[230:233], v[214:217], v[64:67]
	s_setprio 0
	s_mov_b32 m0, s58
	v_lshl_add_u64 v[168:169], v[236:237], 0, s[38:39]
	s_barrier
	ds_read_b128 v[186:189], v161 offset:49152
	ds_read_b128 v[190:193], v161 offset:50176
	ds_read_b128 v[194:197], v161 offset:51200
	ds_read_b128 v[198:201], v161 offset:52224
	ds_read_b128 v[202:205], v161 offset:53248
	ds_read_b128 v[206:209], v161 offset:54272
	ds_read_b128 v[210:213], v161 offset:55296
	ds_read_b128 v[214:217], v161 offset:56320
	global_load_lds_dwordx4 v[168:169], off
	v_lshl_add_u64 v[168:169], v[238:239], 0, s[38:39]
	s_mov_b32 m0, s59
	s_nop 0
	global_load_lds_dwordx4 v[168:169], off
	s_barrier
; #define PG8_STAGE(bufoff, gbase, voff) do { _Pragma("unroll") for (int _i = 0; _i < 2; ++_i) \
;         __builtin_amdgcn_global_load_lds((const unsigned*)((const char*)(gbase) + (voff)[_i]), (LAS unsigned*)(lds + (bufoff) + ldsw + _i * 8192), 16, 0, 0); } while (0)
; #define PG8_MMA(ai, bj, At, Bt) do { __builtin_amdgcn_s_setprio(1); _Pragma("unroll") for (int m = 0; m < 4; ++m) _Pragma("unroll") for (int n = 0; n < 2; ++n) _Pragma("unroll") for (int k = 0; k < 2; ++k) \
;         acc[ai][bj][m][n] = __builtin_amdgcn_mfma_f32_16x16x32_bf16(Bt[n][k], At[m][k], acc[ai][bj][m][n], 0, 0, 0); __builtin_amdgcn_s_setprio(0); } while (0)
; #define PG8_WAIT_V(n) asm volatile("s_waitcnt vmcnt(" #n ")" ::: "memory")
; #define PG8_WAIT_L(n) asm volatile("s_waitcnt lgkmcnt(" #n ")" ::: "memory")
; #define PG8_BAR __builtin_amdgcn_s_barrier()
; #define PG8_SCHED __builtin_amdgcn_sched_barrier(0)
; template <class Epi, class Sched>
; __device__ __forceinline__ void gemm_phase(LAS unsigned char* lds, const int K, const Sched& S, const Epi& E) {
;     ...
;             PG8_BAR; PG8_WAIT_L(0); PG8_MMA(1, 0, At, B0); PG8_BAR; PG8_SCHED;
;             PG8_STAGE(PG8_SB(1, 1), b3 + hstep, voffB);
;             PG8_WAIT_V(6); PG8_BAR; PG8_MMA(1, 1, At, B1); PG8_BAR;
	s_waitcnt lgkmcnt(0)
	s_setprio 1
	s_waitcnt lgkmcnt(0)
	v_mfma_f32_16x16x32_bf16 v[60:63], v[164:167], v[186:189], v[60:63]
	v_mfma_f32_16x16x32_bf16 v[56:59], v[178:181], v[186:189], v[56:59]
	v_mfma_f32_16x16x32_bf16 v[52:55], v[164:167], v[194:197], v[52:55]
	v_mfma_f32_16x16x32_bf16 v[44:47], v[178:181], v[194:197], v[44:47]
	v_mfma_f32_16x16x32_bf16 v[36:39], v[164:167], v[202:205], v[36:39]
	v_mfma_f32_16x16x32_bf16 v[28:31], v[178:181], v[202:205], v[28:31]
	v_mfma_f32_16x16x32_bf16 v[20:23], v[164:167], v[210:213], v[20:23]
	v_mfma_f32_16x16x32_bf16 v[12:15], v[178:181], v[210:213], v[12:15]
	v_mfma_f32_16x16x32_bf16 v[60:63], v[174:177], v[190:193], v[60:63]
	v_mfma_f32_16x16x32_bf16 v[56:59], v[182:185], v[190:193], v[56:59]
	v_mfma_f32_16x16x32_bf16 v[52:55], v[174:177], v[198:201], v[52:55]
	v_mfma_f32_16x16x32_bf16 v[44:47], v[182:185], v[198:201], v[44:47]
	v_mfma_f32_16x16x32_bf16 v[36:39], v[174:177], v[206:209], v[36:39]
	v_mfma_f32_16x16x32_bf16 v[28:31], v[182:185], v[206:209], v[28:31]
	v_mfma_f32_16x16x32_bf16 v[20:23], v[174:177], v[214:217], v[20:23]
	v_mfma_f32_16x16x32_bf16 v[12:15], v[182:185], v[214:217], v[12:15]
	s_setprio 0
	s_barrier
	s_add_u32 s72, s72, 0x40080
	s_addc_u32 s73, s73, 0
	s_add_i32 s74, s74, s54
	v_lshl_add_u64 v[164:165], s[72:73], 0, v[130:131]
	s_mov_b32 m0, s74
	s_nop 0
	global_load_lds_dwordx4 v[164:165], off
	v_lshl_add_u64 v[164:165], s[72:73], 0, v[134:135]
	s_add_i32 m0, s74, 0x2000
	s_nop 0
	global_load_lds_dwordx4 v[164:165], off
	s_waitcnt vmcnt(6)
	s_barrier
	s_setprio 1
	v_mfma_f32_16x16x32_bf16 v[48:51], v[218:221], v[186:189], v[48:51]
	v_mfma_f32_16x16x32_bf16 v[40:43], v[226:229], v[186:189], v[40:43]
	v_mfma_f32_16x16x32_bf16 v[32:35], v[218:221], v[194:197], v[32:35]
	v_mfma_f32_16x16x32_bf16 v[24:27], v[226:229], v[194:197], v[24:27]
	v_mfma_f32_16x16x32_bf16 v[16:19], v[218:221], v[202:205], v[16:19]
	v_mfma_f32_16x16x32_bf16 v[8:11], v[226:229], v[202:205], v[8:11]
	v_mfma_f32_16x16x32_bf16 v[4:7], v[218:221], v[210:213], v[4:7]
	v_mfma_f32_16x16x32_bf16 v[0:3], v[226:229], v[210:213], v[0:3]
	v_mfma_f32_16x16x32_bf16 v[48:51], v[222:225], v[190:193], v[48:51]
	v_mfma_f32_16x16x32_bf16 v[40:43], v[230:233], v[190:193], v[40:43]
	v_mfma_f32_16x16x32_bf16 v[32:35], v[222:225], v[198:201], v[32:35]
	v_mfma_f32_16x16x32_bf16 v[24:27], v[230:233], v[198:201], v[24:27]
	v_mfma_f32_16x16x32_bf16 v[16:19], v[222:225], v[206:209], v[16:19]
	v_mfma_f32_16x16x32_bf16 v[8:11], v[230:233], v[206:209], v[8:11]
	v_mfma_f32_16x16x32_bf16 v[4:7], v[222:225], v[214:217], v[4:7]
	v_mfma_f32_16x16x32_bf16 v[0:3], v[230:233], v[214:217], v[0:3]
	s_setprio 0
	s_add_i32 s67, s67, 2
	s_add_u32 s70, s70, 0x100
	s_addc_u32 s71, s71, 0
	s_add_u32 s43, s43, 0x100
	s_addc_u32 s65, s65, 0
	s_cmp_gt_u32 s67, 13
	s_barrier
	s_cbranch_scc0 .LBB0_189
; __device__ __forceinline__ unsigned cvt_pk_bf16(float lo, float hi) { unsigned r; asm volatile("v_cvt_pk_bf16_f32 %0, %1, %2" : "=v"(r) : "v"(lo), "v"(hi)); return r; }
;     __device__ __forceinline__ void operator()(const f32x4 (&acc)[2][2][4][2], const Unit& u, int wr, int wc, int fr, int fq) const {
;         bf16_t* base = (bf16_t*)u.po + (size_t)wr * u.RS + (size_t)fr * u.rp + (size_t)(wc >> 1) * u.CS + (wc & 1) * 32 + 8 * fq;
; #pragma unroll
;         for (int ai = 0; ai < 2; ++ai)
; #pragma unroll
;             for (int m = 0; m < 4; ++m) { bf16_t* rowp = base + (size_t)(2 * ai) * u.RS + (size_t)(m * 16) * u.rp;
; #pragma unroll
;                 for (int bj = 0; bj < 2; ++bj) { const f32x4 v0 = acc[ai][bj][m][0], v1 = acc[ai][bj][m][1];
;                     u32x4 w; w.x = cvt_pk_bf16(v0[0], v0[1]); w.y = cvt_pk_bf16(v0[2], v0[3]); w.z = cvt_pk_bf16(v1[0], v1[1]); w.w = cvt_pk_bf16(v1[2], v1[3]);
;                     *(u32x4*)(rowp + (size_t)(2 * bj) * u.CS) = w; } }
;         if (u.sp) {
; #pragma unroll
;             for (int ai = 0; ai < 2; ++ai)
; #pragma unroll
;                 for (int m = 0; m < 4; ++m) { float s = 0.f;
; #pragma unroll
;                     for (int bj = 0; bj < 2; ++bj)
; #pragma unroll
;                         for (int n = 0; n < 2; ++n) { const f32x4 v = acc[ai][bj][m][n]; s += (v[0] - v[1]) + (v[2] - v[3]); }
;                     s += __shfl_xor(s, 16); s += __shfl_xor(s, 32);
;                     if (fq == 0) u.sp[(size_t)(ai * HALF + wr * 64 + m * 16 + fr) * 32 + wc] = s; }
	s_mul_hi_i32 s71, s42, s97
	s_mul_i32 s70, s42, s97
	s_ashr_i32 s43, s42, 31
	s_lshl_b64 s[70:71], s[70:71], 1
	s_add_u32 s68, s68, s70
	s_addc_u32 s69, s69, s71
	v_mad_i64_i32 v[164:165], s[70:71], s66, v138, 0
	v_lshl_add_u64 v[164:165], v[164:165], 1, s[68:69]
	s_mul_hi_i32 s69, s64, s87
	s_mul_i32 s68, s64, s87
	v_lshl_add_u64 v[164:165], s[68:69], 1, v[164:165]
	s_ashr_i32 s65, s64, 31
	v_lshl_add_u64 v[164:165], v[164:165], 0, s[6:7]
	s_ashr_i32 s67, s66, 31
	v_lshl_add_u64 v[168:169], v[164:165], 0, v[136:137]
	v_cvt_pk_bf16_f32 v164, v124, v125
	v_cvt_pk_bf16_f32 v165, v126, v127
	v_cvt_pk_bf16_f32 v166, v120, v121
	v_cvt_pk_bf16_f32 v167, v122, v123
	s_lshl_b64 s[64:65], s[64:65], 2
	global_store_dwordx4 v[168:169], v[164:167], off sc1
	v_lshl_add_u64 v[174:175], v[168:169], 0, s[64:65]
	s_lshl_b64 s[66:67], s[66:67], 5
	v_cvt_pk_bf16_f32 v164, v116, v117
	v_cvt_pk_bf16_f32 v165, v118, v119
	v_cvt_pk_bf16_f32 v166, v108, v109
	v_cvt_pk_bf16_f32 v167, v110, v111
	global_store_dwordx4 v[174:175], v[164:167], off sc1
	v_lshl_add_u64 v[174:175], v[168:169], 0, s[66:67]
	v_lshl_add_u64 v[176:177], v[174:175], 0, s[64:65]
	v_cvt_pk_bf16_f32 v164, v112, v113
	v_cvt_pk_bf16_f32 v165, v114, v115
	v_cvt_pk_bf16_f32 v166, v104, v105
	v_cvt_pk_bf16_f32 v167, v106, v107
	global_store_dwordx4 v[174:175], v[164:167], off sc1
	v_lshl_add_u64 v[174:175], v[174:175], 0, s[66:67]
	v_lshl_add_u64 v[168:169], s[42:43], 2, v[168:169]
	v_cvt_pk_bf16_f32 v164, v96, v97
	v_cvt_pk_bf16_f32 v165, v98, v99
	v_cvt_pk_bf16_f32 v166, v88, v89
	v_cvt_pk_bf16_f32 v167, v90, v91
	global_store_dwordx4 v[176:177], v[164:167], off sc1
	v_lshl_add_u64 v[176:177], v[174:175], 0, s[64:65]
	s_cmp_eq_u64 s[8:9], 0
	v_cvt_pk_bf16_f32 v164, v100, v101
	v_cvt_pk_bf16_f32 v165, v102, v103
	v_cvt_pk_bf16_f32 v166, v92, v93
	v_cvt_pk_bf16_f32 v167, v94, v95
	global_store_dwordx4 v[174:175], v[164:167], off sc1
	v_lshl_add_u64 v[174:175], v[174:175], 0, s[66:67]
	s_nop 0
	v_cvt_pk_bf16_f32 v164, v80, v81
	v_cvt_pk_bf16_f32 v165, v82, v83
	v_cvt_pk_bf16_f32 v166, v72, v73
	v_cvt_pk_bf16_f32 v167, v74, v75
	global_store_dwordx4 v[176:177], v[164:167], off sc1
	s_nop 1
	v_cvt_pk_bf16_f32 v164, v84, v85
	v_cvt_pk_bf16_f32 v165, v86, v87
	v_cvt_pk_bf16_f32 v166, v76, v77
	v_cvt_pk_bf16_f32 v167, v78, v79
	global_store_dwordx4 v[174:175], v[164:167], off sc1
	v_lshl_add_u64 v[174:175], v[174:175], 0, s[64:65]
	s_nop 0
	v_cvt_pk_bf16_f32 v164, v68, v69
	v_cvt_pk_bf16_f32 v165, v70, v71
	v_cvt_pk_bf16_f32 v166, v64, v65
	v_cvt_pk_bf16_f32 v167, v66, v67
	global_store_dwordx4 v[174:175], v[164:167], off sc1
	v_lshl_add_u64 v[174:175], v[168:169], 0, s[64:65]
	s_nop 0
	v_cvt_pk_bf16_f32 v164, v60, v61
	v_cvt_pk_bf16_f32 v165, v62, v63
	v_cvt_pk_bf16_f32 v166, v56, v57
	v_cvt_pk_bf16_f32 v167, v58, v59
	global_store_dwordx4 v[168:169], v[164:167], off sc1
	v_lshl_add_u64 v[168:169], v[168:169], 0, s[66:67]
	s_nop 0
	v_cvt_pk_bf16_f32 v164, v48, v49
	v_cvt_pk_bf16_f32 v165, v50, v51
	v_cvt_pk_bf16_f32 v166, v40, v41
	v_cvt_pk_bf16_f32 v167, v42, v43
	global_store_dwordx4 v[174:175], v[164:167], off sc1
	v_lshl_add_u64 v[174:175], v[168:169], 0, s[64:65]
	s_nop 0
	v_cvt_pk_bf16_f32 v164, v52, v53
	v_cvt_pk_bf16_f32 v165, v54, v55
	v_cvt_pk_bf16_f32 v166, v44, v45
	v_cvt_pk_bf16_f32 v167, v46, v47
	global_store_dwordx4 v[168:169], v[164:167], off sc1
	v_lshl_add_u64 v[168:169], v[168:169], 0, s[66:67]
	s_nop 0
	v_cvt_pk_bf16_f32 v164, v32, v33
	v_cvt_pk_bf16_f32 v165, v34, v35
	v_cvt_pk_bf16_f32 v166, v24, v25
	v_cvt_pk_bf16_f32 v167, v26, v27
	global_store_dwordx4 v[174:175], v[164:167], off sc1
	v_lshl_add_u64 v[174:175], v[168:169], 0, s[64:65]
	s_nop 0
	v_cvt_pk_bf16_f32 v164, v36, v37
	v_cvt_pk_bf16_f32 v165, v38, v39
	v_cvt_pk_bf16_f32 v166, v28, v29
	v_cvt_pk_bf16_f32 v167, v30, v31
	global_store_dwordx4 v[168:169], v[164:167], off sc1
	v_lshl_add_u64 v[168:169], v[168:169], 0, s[66:67]
	s_nop 0
	v_cvt_pk_bf16_f32 v164, v16, v17
	v_cvt_pk_bf16_f32 v165, v18, v19
	v_cvt_pk_bf16_f32 v166, v8, v9
	v_cvt_pk_bf16_f32 v167, v10, v11
	global_store_dwordx4 v[174:175], v[164:167], off sc1
	s_nop 1
	v_cvt_pk_bf16_f32 v164, v20, v21
	v_cvt_pk_bf16_f32 v165, v22, v23
	v_cvt_pk_bf16_f32 v166, v12, v13
	v_cvt_pk_bf16_f32 v167, v14, v15
	global_store_dwordx4 v[168:169], v[164:167], off sc1
	v_lshl_add_u64 v[168:169], v[168:169], 0, s[64:65]
	s_nop 0
	v_cvt_pk_bf16_f32 v164, v4, v5
	v_cvt_pk_bf16_f32 v165, v6, v7
	v_cvt_pk_bf16_f32 v166, v0, v1
	v_cvt_pk_bf16_f32 v167, v2, v3
	global_store_dwordx4 v[168:169], v[164:167], off sc1
	s_cbranch_scc1 .LBB0_175
	v_sub_f32_e32 v124, v124, v125
	v_sub_f32_e32 v125, v126, v127
	v_and_b32_e32 v165, 64, v163
	v_add_f32_e32 v124, v124, v125
	v_sub_f32_e32 v120, v120, v121
	v_sub_f32_e32 v121, v122, v123
	v_xor_b32_e32 v164, 16, v163
	v_add_u32_e32 v165, 64, v165
	v_add_f32_e32 v124, 0, v124
	v_add_f32_e32 v120, v120, v121
	v_sub_f32_e32 v116, v116, v117
	v_sub_f32_e32 v117, v118, v119
	v_cmp_lt_i32_e32 vcc, v164, v165
	v_add_f32_e32 v120, v124, v120
	v_add_f32_e32 v116, v116, v117
	v_sub_f32_e32 v108, v108, v109
	v_sub_f32_e32 v109, v110, v111
	v_cndmask_b32_e32 v164, v163, v164, vcc
	v_add_f32_e32 v116, v120, v116
	v_add_f32_e32 v108, v108, v109
	v_lshlrev_b32_e32 v164, 2, v164
	v_add_f32_e32 v109, v116, v108
	ds_bpermute_b32 v110, v164, v109
	v_xor_b32_e32 v108, 32, v163
	v_cmp_lt_i32_e32 vcc, v108, v165
	s_add_u32 s8, s8, s53
	s_addc_u32 s9, s9, 0
	v_cndmask_b32_e32 v108, v163, v108, vcc
	v_lshlrev_b32_e32 v108, 2, v108
	s_waitcnt lgkmcnt(0)
	v_add_f32_e32 v109, v109, v110
	ds_bpermute_b32 v110, v108, v109
	s_and_saveexec_b64 s[42:43], s[0:1]
	s_cbranch_execz .LBB0_193
	s_waitcnt lgkmcnt(0)
	v_add_f32_e32 v109, v109, v110
	v_lshl_add_u64 v[110:111], s[8:9], 0, v[140:141]
	global_store_dword v[110:111], v109, off

; #define PG8_STAGE(bufoff, gbase, voff) do { _Pragma("unroll") for (int _i = 0; _i < 2; ++_i) \
;         __builtin_amdgcn_global_load_lds((const unsigned*)((const char*)(gbase) + (voff)[_i]), (LAS unsigned*)(lds + (bufoff) + ldsw + _i * 8192), 16, 0, 0); } while (0)
; #define PG8_LDA(dst, b, h) do { _Pragma("unroll") for (int m = 0; m < 4; ++m) _Pragma("unroll") for (int k = 0; k < 2; ++k) dst[m][k] = *(const LAS bf16x8*)(lds + PG8_SA(b, h) + aoff + m * 2048 + k * 1024); } while (0)
; #define PG8_LDB(dst, b, h) do { _Pragma("unroll") for (int n = 0; n < 2; ++n) _Pragma("unroll") for (int k = 0; k < 2; ++k) dst[n][k] = *(const LAS bf16x8*)(lds + PG8_SB(b, h) + boff + n * 2048 + k * 1024); } while (0)
; #define PG8_MMA(ai, bj, At, Bt) do { __builtin_amdgcn_s_setprio(1); _Pragma("unroll") for (int m = 0; m < 4; ++m) _Pragma("unroll") for (int n = 0; n < 2; ++n) _Pragma("unroll") for (int k = 0; k < 2; ++k) \
;         acc[ai][bj][m][n] = __builtin_amdgcn_mfma_f32_16x16x32_bf16(Bt[n][k], At[m][k], acc[ai][bj][m][n], 0, 0, 0); __builtin_amdgcn_s_setprio(0); } while (0)
; #define PG8_WAIT_V(n) asm volatile("s_waitcnt vmcnt(" #n ")" ::: "memory")
; #define PG8_WAIT_L(n) asm volatile("s_waitcnt lgkmcnt(" #n ")" ::: "memory")
; template <class Epi, class Sched>
; __device__ __forceinline__ void gemm_phase(LAS unsigned char* lds, const int K, const Sched& S, const Epi& E) {
;     ...
;         for (int t = 0; t < nt; t += 2) {
;             const bool last = (t == nt - 2);
;             const char* a1 = cA + (size_t)(t + 1) * kstep;
;             const char* a2 = last ? nA : cA + (size_t)(t + 2) * kstep; const char* b2 = last ? nB : cB + (size_t)(t + 2) * kstep;
;             const char* a3 = a2 + kstep; const char* b3 = b2 + kstep;
;             PG8_LDB(B0, 0, 0); PG8_SCHED; PG8_LDA(At, 0, 0); PG8_STAGE(PG8_SA(1, 1), a1 + hstepA, voffA);
;             PG8_WAIT_L(8); PG8_BAR; PG8_WAIT_L(0); PG8_MMA(0, 0, At, B0); PG8_BAR; PG8_SCHED;
;             PG8_LDB(B1, 0, 1); PG8_STAGE(PG8_SB(0, 0), b2, voffB);
;             PG8_BAR; PG8_WAIT_L(0); PG8_MMA(0, 1, At, B1); PG8_BAR;
;             PG8_LDA(At, 0, 1); PG8_STAGE(PG8_SA(0, 0), a2, voffA);
;             PG8_BAR; PG8_WAIT_L(0); PG8_MMA(1, 0, At, B0); PG8_BAR; PG8_SCHED;
;             PG8_STAGE(PG8_SB(0, 1), b2 + hstep, voffB);
;             PG8_WAIT_V(6); PG8_BAR; PG8_MMA(1, 1, At, B1); PG8_BAR;
.LBB0_299:
	ds_read_b128 v[156:159], v153
	ds_read_b128 v[160:163], v153 offset:1024
	ds_read_b128 v[164:167], v153 offset:2048
	ds_read_b128 v[174:177], v153 offset:3072
	s_add_u32 s66, s64, 0xfffc0080
	s_addc_u32 s67, s65, -1
	s_cmp_eq_u32 s83, 12
	s_cselect_b32 s69, s45, s67
	s_cselect_b32 s68, s44, s66
	s_cselect_b32 s67, s47, s82
	s_cselect_b32 s66, s46, s41
	v_lshl_add_u64 v[150:151], s[64:65], 0, v[144:145]
	s_add_i32 m0, s54, 0xc000
	ds_read_b128 v[178:181], v154
	ds_read_b128 v[182:185], v154 offset:1024
	ds_read_b128 v[186:189], v154 offset:2048
	ds_read_b128 v[190:193], v154 offset:3072
	ds_read_b128 v[194:197], v154 offset:4096
	ds_read_b128 v[198:201], v154 offset:5120
	ds_read_b128 v[202:205], v154 offset:6144
	ds_read_b128 v[206:209], v154 offset:7168
	global_load_lds_dwordx4 v[150:151], off
	v_lshl_add_u64 v[150:151], s[64:65], 0, v[146:147]
	s_add_i32 m0, s54, 0xe000
	s_nop 0
	global_load_lds_dwordx4 v[150:151], off
	s_waitcnt lgkmcnt(8)
	s_barrier
	s_waitcnt lgkmcnt(0)
	s_setprio 1
	s_waitcnt lgkmcnt(0)
	v_mfma_f32_16x16x32_bf16 v[124:127], v[156:159], v[178:181], v[124:127]
	v_mfma_f32_16x16x32_bf16 v[120:123], v[164:167], v[178:181], v[120:123]
	v_mfma_f32_16x16x32_bf16 v[116:119], v[156:159], v[186:189], v[116:119]
	v_mfma_f32_16x16x32_bf16 v[108:111], v[164:167], v[186:189], v[108:111]
	v_mfma_f32_16x16x32_bf16 v[100:103], v[156:159], v[194:197], v[100:103]
	v_mfma_f32_16x16x32_bf16 v[92:95], v[164:167], v[194:197], v[92:95]
	v_mfma_f32_16x16x32_bf16 v[84:87], v[156:159], v[202:205], v[84:87]
	v_mfma_f32_16x16x32_bf16 v[76:79], v[164:167], v[202:205], v[76:79]
	v_mfma_f32_16x16x32_bf16 v[124:127], v[160:163], v[182:185], v[124:127]
	v_mfma_f32_16x16x32_bf16 v[120:123], v[174:177], v[182:185], v[120:123]
	v_mfma_f32_16x16x32_bf16 v[116:119], v[160:163], v[190:193], v[116:119]
	v_mfma_f32_16x16x32_bf16 v[108:111], v[174:177], v[190:193], v[108:111]
	v_mfma_f32_16x16x32_bf16 v[100:103], v[160:163], v[198:201], v[100:103]
	v_mfma_f32_16x16x32_bf16 v[92:95], v[174:177], v[198:201], v[92:95]
	v_mfma_f32_16x16x32_bf16 v[84:87], v[160:163], v[206:209], v[84:87]
	v_mfma_f32_16x16x32_bf16 v[76:79], v[174:177], v[206:209], v[76:79]
	s_setprio 0
	s_barrier
	s_add_i32 s84, s72, s53
	v_lshl_add_u64 v[150:151], s[66:67], 0, v[136:137]
	s_mov_b32 m0, s84
	ds_read_b128 v[210:213], v155
	ds_read_b128 v[214:217], v155 offset:1024
	ds_read_b128 v[218:221], v155 offset:2048
	ds_read_b128 v[222:225], v155 offset:3072
	global_load_lds_dwordx4 v[150:151], off
	v_lshl_add_u64 v[168:169], s[66:67], 0, v[140:141]
	s_add_i32 m0, s84, 0x2000
	s_nop 0
	global_load_lds_dwordx4 v[168:169], off
	s_barrier
	s_waitcnt lgkmcnt(0)
	s_setprio 1
	s_waitcnt lgkmcnt(0)
	v_mfma_f32_16x16x32_bf16 v[112:115], v[210:213], v[178:181], v[112:115]
	v_mfma_f32_16x16x32_bf16 v[104:107], v[218:221], v[178:181], v[104:107]
	v_mfma_f32_16x16x32_bf16 v[96:99], v[210:213], v[186:189], v[96:99]
	v_mfma_f32_16x16x32_bf16 v[88:91], v[218:221], v[186:189], v[88:91]
	v_mfma_f32_16x16x32_bf16 v[80:83], v[210:213], v[194:197], v[80:83]
	v_mfma_f32_16x16x32_bf16 v[72:75], v[218:221], v[194:197], v[72:75]
	v_mfma_f32_16x16x32_bf16 v[68:71], v[210:213], v[202:205], v[68:71]
	v_mfma_f32_16x16x32_bf16 v[64:67], v[218:221], v[202:205], v[64:67]
	v_mfma_f32_16x16x32_bf16 v[112:115], v[214:217], v[182:185], v[112:115]
	v_mfma_f32_16x16x32_bf16 v[104:107], v[222:225], v[182:185], v[104:107]
	v_mfma_f32_16x16x32_bf16 v[96:99], v[214:217], v[190:193], v[96:99]
	v_mfma_f32_16x16x32_bf16 v[88:91], v[222:225], v[190:193], v[88:91]
	v_mfma_f32_16x16x32_bf16 v[80:83], v[214:217], v[198:201], v[80:83]
	v_mfma_f32_16x16x32_bf16 v[72:75], v[222:225], v[198:201], v[72:75]
	v_mfma_f32_16x16x32_bf16 v[68:71], v[214:217], v[206:209], v[68:71]
	v_mfma_f32_16x16x32_bf16 v[64:67], v[222:225], v[206:209], v[64:67]
	s_setprio 0
	s_mov_b32 m0, s54
	v_lshl_add_u64 v[226:227], s[68:69], 0, v[134:135]
	s_barrier
	ds_read_b128 v[178:181], v154 offset:16384
	ds_read_b128 v[182:185], v154 offset:17408
	ds_read_b128 v[186:189], v154 offset:18432
	ds_read_b128 v[190:193], v154 offset:19456
	ds_read_b128 v[194:197], v154 offset:20480
	ds_read_b128 v[198:201], v154 offset:21504
	ds_read_b128 v[202:205], v154 offset:22528
	ds_read_b128 v[206:209], v154 offset:23552
	global_load_lds_dwordx4 v[226:227], off
	v_lshl_add_u64 v[228:229], s[68:69], 0, v[138:139]
	s_mov_b32 m0, s55
	s_nop 0
	global_load_lds_dwordx4 v[228:229], off
	s_barrier
	s_waitcnt lgkmcnt(0)
	s_setprio 1
	s_waitcnt lgkmcnt(0)
	v_mfma_f32_16x16x32_bf16 v[60:63], v[156:159], v[178:181], v[60:63]
	v_mfma_f32_16x16x32_bf16 v[56:59], v[164:167], v[178:181], v[56:59]
	v_mfma_f32_16x16x32_bf16 v[52:55], v[156:159], v[186:189], v[52:55]
	v_mfma_f32_16x16x32_bf16 v[44:47], v[164:167], v[186:189], v[44:47]
	v_mfma_f32_16x16x32_bf16 v[36:39], v[156:159], v[194:197], v[36:39]
	v_mfma_f32_16x16x32_bf16 v[28:31], v[164:167], v[194:197], v[28:31]
	v_mfma_f32_16x16x32_bf16 v[20:23], v[156:159], v[202:205], v[20:23]
	v_mfma_f32_16x16x32_bf16 v[12:15], v[164:167], v[202:205], v[12:15]
	v_mfma_f32_16x16x32_bf16 v[60:63], v[160:163], v[182:185], v[60:63]
	v_mfma_f32_16x16x32_bf16 v[56:59], v[174:177], v[182:185], v[56:59]
	v_mfma_f32_16x16x32_bf16 v[52:55], v[160:163], v[190:193], v[52:55]
	v_mfma_f32_16x16x32_bf16 v[44:47], v[174:177], v[190:193], v[44:47]
	v_mfma_f32_16x16x32_bf16 v[36:39], v[160:163], v[198:201], v[36:39]
	v_mfma_f32_16x16x32_bf16 v[28:31], v[174:177], v[198:201], v[28:31]
	v_mfma_f32_16x16x32_bf16 v[20:23], v[160:163], v[206:209], v[20:23]
	v_mfma_f32_16x16x32_bf16 v[12:15], v[174:177], v[206:209], v[12:15]
	s_setprio 0
	s_barrier
; #define PG8_STAGE(bufoff, gbase, voff) do { _Pragma("unroll") for (int _i = 0; _i < 2; ++_i) \
;         __builtin_amdgcn_global_load_lds((const unsigned*)((const char*)(gbase) + (voff)[_i]), (LAS unsigned*)(lds + (bufoff) + ldsw + _i * 8192), 16, 0, 0); } while (0)
; #define PG8_LDA(dst, b, h) do { _Pragma("unroll") for (int m = 0; m < 4; ++m) _Pragma("unroll") for (int k = 0; k < 2; ++k) dst[m][k] = *(const LAS bf16x8*)(lds + PG8_SA(b, h) + aoff + m * 2048 + k * 1024); } while (0)
; #define PG8_LDB(dst, b, h) do { _Pragma("unroll") for (int n = 0; n < 2; ++n) _Pragma("unroll") for (int k = 0; k < 2; ++k) dst[n][k] = *(const LAS bf16x8*)(lds + PG8_SB(b, h) + boff + n * 2048 + k * 1024); } while (0)
; #define PG8_MMA(ai, bj, At, Bt) do { __builtin_amdgcn_s_setprio(1); _Pragma("unroll") for (int m = 0; m < 4; ++m) _Pragma("unroll") for (int n = 0; n < 2; ++n) _Pragma("unroll") for (int k = 0; k < 2; ++k) \
;         acc[ai][bj][m][n] = __builtin_amdgcn_mfma_f32_16x16x32_bf16(Bt[n][k], At[m][k], acc[ai][bj][m][n], 0, 0, 0); __builtin_amdgcn_s_setprio(0); } while (0)
; #define PG8_WAIT_V(n) asm volatile("s_waitcnt vmcnt(" #n ")" ::: "memory")
; #define PG8_WAIT_L(n) asm volatile("s_waitcnt lgkmcnt(" #n ")" ::: "memory")
; #define PG8_BAR __builtin_amdgcn_s_barrier()
; #define PG8_SCHED __builtin_amdgcn_sched_barrier(0)
; template <class Epi, class Sched>
; __device__ __forceinline__ void gemm_phase(LAS unsigned char* lds, const int K, const Sched& S, const Epi& E) {
;     ...
;             PG8_STAGE(PG8_SB(0, 1), b2 + hstep, voffB);
;             PG8_WAIT_V(6); PG8_BAR; PG8_MMA(1, 1, At, B1); PG8_BAR;
;             PG8_LDB(B0, 1, 0); PG8_SCHED; PG8_LDA(At, 1, 0); PG8_STAGE(PG8_SA(0, 1), a2 + hstepA, voffA);
;             PG8_WAIT_L(8); PG8_BAR; PG8_WAIT_L(0); PG8_MMA(0, 0, At, B0); PG8_BAR; PG8_SCHED;
;             PG8_LDB(B1, 1, 1); PG8_STAGE(PG8_SB(1, 0), b3, voffB);
;             PG8_BAR; PG8_WAIT_L(0); PG8_MMA(0, 1, At, B1); PG8_BAR;
;             PG8_LDA(At, 1, 1); PG8_STAGE(PG8_SA(1, 0), a3, voffA);
;             PG8_BAR; PG8_WAIT_L(0); PG8_MMA(1, 0, At, B0); PG8_BAR; PG8_SCHED;
	s_add_u32 s84, s66, 0x40000
	s_addc_u32 s85, s67, 0
	s_add_i32 s86, s73, s53
	v_lshl_add_u64 v[156:157], s[84:85], 0, v[136:137]
	s_mov_b32 m0, s86
	s_nop 0
	global_load_lds_dwordx4 v[156:157], off
	v_lshl_add_u64 v[156:157], s[84:85], 0, v[140:141]
	s_add_i32 m0, s86, 0x2000
	s_nop 0
	global_load_lds_dwordx4 v[156:157], off
	s_waitcnt vmcnt(6)
	s_barrier
	s_setprio 1
	v_mfma_f32_16x16x32_bf16 v[48:51], v[210:213], v[178:181], v[48:51]
	v_mfma_f32_16x16x32_bf16 v[40:43], v[218:221], v[178:181], v[40:43]
	v_mfma_f32_16x16x32_bf16 v[32:35], v[210:213], v[186:189], v[32:35]
	v_mfma_f32_16x16x32_bf16 v[24:27], v[218:221], v[186:189], v[24:27]
	v_mfma_f32_16x16x32_bf16 v[16:19], v[210:213], v[194:197], v[16:19]
	v_mfma_f32_16x16x32_bf16 v[8:11], v[218:221], v[194:197], v[8:11]
	v_mfma_f32_16x16x32_bf16 v[4:7], v[210:213], v[202:205], v[4:7]
	v_mfma_f32_16x16x32_bf16 v[0:3], v[218:221], v[202:205], v[0:3]
	v_mfma_f32_16x16x32_bf16 v[48:51], v[214:217], v[182:185], v[48:51]
	v_mfma_f32_16x16x32_bf16 v[40:43], v[222:225], v[182:185], v[40:43]
	v_mfma_f32_16x16x32_bf16 v[32:35], v[214:217], v[190:193], v[32:35]
	v_mfma_f32_16x16x32_bf16 v[24:27], v[222:225], v[190:193], v[24:27]
	v_mfma_f32_16x16x32_bf16 v[16:19], v[214:217], v[198:201], v[16:19]
	v_mfma_f32_16x16x32_bf16 v[8:11], v[222:225], v[198:201], v[8:11]
	v_mfma_f32_16x16x32_bf16 v[4:7], v[214:217], v[206:209], v[4:7]
	v_mfma_f32_16x16x32_bf16 v[0:3], v[222:225], v[206:209], v[0:3]
	s_setprio 0
	s_add_i32 s84, 0, 0x18000
	v_add_u32_e32 v149, s84, v152
	s_barrier
	ds_read_b128 v[156:159], v149
	ds_read_b128 v[160:163], v149 offset:1024
	ds_read_b128 v[164:167], v149 offset:2048
	ds_read_b128 v[174:177], v149 offset:3072
	s_add_u32 s68, s68, 0x40000
	s_addc_u32 s69, s69, 0
	s_mov_b32 m0, s56
	v_lshl_add_u64 v[210:211], s[68:69], 0, v[134:135]
	ds_read_b128 v[178:181], v154 offset:32768
	ds_read_b128 v[182:185], v154 offset:33792
	ds_read_b128 v[186:189], v154 offset:34816
	ds_read_b128 v[190:193], v154 offset:35840
	ds_read_b128 v[194:197], v154 offset:36864
	ds_read_b128 v[198:201], v154 offset:37888
	ds_read_b128 v[202:205], v154 offset:38912
	ds_read_b128 v[206:209], v154 offset:39936
	global_load_lds_dwordx4 v[210:211], off
	v_lshl_add_u64 v[210:211], s[68:69], 0, v[138:139]
	s_mov_b32 m0, s57
	s_nop 0
	global_load_lds_dwordx4 v[210:211], off
	s_waitcnt lgkmcnt(8)
	s_barrier
	s_waitcnt lgkmcnt(0)
	s_setprio 1
	s_waitcnt lgkmcnt(0)
	v_mfma_f32_16x16x32_bf16 v[124:127], v[156:159], v[178:181], v[124:127]
	v_mfma_f32_16x16x32_bf16 v[120:123], v[164:167], v[178:181], v[120:123]
	v_mfma_f32_16x16x32_bf16 v[116:119], v[156:159], v[186:189], v[116:119]
	v_mfma_f32_16x16x32_bf16 v[108:111], v[164:167], v[186:189], v[108:111]
	v_mfma_f32_16x16x32_bf16 v[100:103], v[156:159], v[194:197], v[100:103]
	v_mfma_f32_16x16x32_bf16 v[92:95], v[164:167], v[194:197], v[92:95]
	v_mfma_f32_16x16x32_bf16 v[84:87], v[156:159], v[202:205], v[84:87]
	v_mfma_f32_16x16x32_bf16 v[76:79], v[164:167], v[202:205], v[76:79]
	v_mfma_f32_16x16x32_bf16 v[124:127], v[160:163], v[182:185], v[124:127]
	v_mfma_f32_16x16x32_bf16 v[120:123], v[174:177], v[182:185], v[120:123]
	v_mfma_f32_16x16x32_bf16 v[116:119], v[160:163], v[190:193], v[116:119]
	v_mfma_f32_16x16x32_bf16 v[108:111], v[174:177], v[190:193], v[108:111]
	v_mfma_f32_16x16x32_bf16 v[100:103], v[160:163], v[198:201], v[100:103]
	v_mfma_f32_16x16x32_bf16 v[92:95], v[174:177], v[198:201], v[92:95]
	v_mfma_f32_16x16x32_bf16 v[84:87], v[160:163], v[206:209], v[84:87]
	v_mfma_f32_16x16x32_bf16 v[76:79], v[174:177], v[206:209], v[76:79]
	s_setprio 0
	s_barrier
	s_add_i32 s68, 0, 0x1c000
	s_add_i32 s69, s84, s53
	v_add_u32_e32 v149, s68, v152
	v_lshl_add_u64 v[150:151], v[150:151], 0, s[6:7]
	s_mov_b32 m0, s69
	ds_read_b128 v[210:213], v149
	ds_read_b128 v[214:217], v149 offset:1024
	ds_read_b128 v[218:221], v149 offset:2048
	ds_read_b128 v[222:225], v149 offset:3072
	global_load_lds_dwordx4 v[150:151], off
	v_lshl_add_u64 v[150:151], v[168:169], 0, s[6:7]
	s_add_i32 m0, s69, 0x2000
	s_nop 0
	global_load_lds_dwordx4 v[150:151], off
	s_barrier
	s_waitcnt lgkmcnt(0)
	s_setprio 1
	s_waitcnt lgkmcnt(0)
	v_mfma_f32_16x16x32_bf16 v[112:115], v[210:213], v[178:181], v[112:115]
	v_mfma_f32_16x16x32_bf16 v[104:107], v[218:221], v[178:181], v[104:107]
	v_mfma_f32_16x16x32_bf16 v[96:99], v[210:213], v[186:189], v[96:99]
	v_mfma_f32_16x16x32_bf16 v[88:91], v[218:221], v[186:189], v[88:91]
	v_mfma_f32_16x16x32_bf16 v[80:83], v[210:213], v[194:197], v[80:83]
	v_mfma_f32_16x16x32_bf16 v[72:75], v[218:221], v[194:197], v[72:75]
	v_mfma_f32_16x16x32_bf16 v[68:71], v[210:213], v[202:205], v[68:71]
	v_mfma_f32_16x16x32_bf16 v[64:67], v[218:221], v[202:205], v[64:67]
	v_mfma_f32_16x16x32_bf16 v[112:115], v[214:217], v[182:185], v[112:115]
	v_mfma_f32_16x16x32_bf16 v[104:107], v[222:225], v[182:185], v[104:107]
	v_mfma_f32_16x16x32_bf16 v[96:99], v[214:217], v[190:193], v[96:99]
	v_mfma_f32_16x16x32_bf16 v[88:91], v[222:225], v[190:193], v[88:91]
	v_mfma_f32_16x16x32_bf16 v[80:83], v[214:217], v[198:201], v[80:83]
	v_mfma_f32_16x16x32_bf16 v[72:75], v[222:225], v[198:201], v[72:75]
	v_mfma_f32_16x16x32_bf16 v[68:71], v[214:217], v[206:209], v[68:71]
	v_mfma_f32_16x16x32_bf16 v[64:67], v[222:225], v[206:209], v[64:67]
	s_setprio 0
	s_mov_b32 m0, s70
	v_lshl_add_u64 v[150:151], v[226:227], 0, s[6:7]
	s_barrier
	ds_read_b128 v[178:181], v154 offset:49152
	ds_read_b128 v[182:185], v154 offset:50176
	ds_read_b128 v[186:189], v154 offset:51200
	ds_read_b128 v[190:193], v154 offset:52224
	ds_read_b128 v[194:197], v154 offset:53248
	ds_read_b128 v[198:201], v154 offset:54272
	ds_read_b128 v[202:205], v154 offset:55296
	ds_read_b128 v[206:209], v154 offset:56320
	global_load_lds_dwordx4 v[150:151], off
	v_lshl_add_u64 v[150:151], v[228:229], 0, s[6:7]
	s_mov_b32 m0, s71
	s_nop 0
	global_load_lds_dwordx4 v[150:151], off
	s_barrier
; __device__ __forceinline__ unsigned cvt_pk_bf16(float lo, float hi) { unsigned r; asm volatile("v_cvt_pk_bf16_f32 %0, %1, %2" : "=v"(r) : "v"(lo), "v"(hi)); return r; }
; #define PG8_STAGE(bufoff, gbase, voff) do { _Pragma("unroll") for (int _i = 0; _i < 2; ++_i) \
;         __builtin_amdgcn_global_load_lds((const unsigned*)((const char*)(gbase) + (voff)[_i]), (LAS unsigned*)(lds + (bufoff) + ldsw + _i * 8192), 16, 0, 0); } while (0)
; #define PG8_MMA(ai, bj, At, Bt) do { __builtin_amdgcn_s_setprio(1); _Pragma("unroll") for (int m = 0; m < 4; ++m) _Pragma("unroll") for (int n = 0; n < 2; ++n) _Pragma("unroll") for (int k = 0; k < 2; ++k) \
;         acc[ai][bj][m][n] = __builtin_amdgcn_mfma_f32_16x16x32_bf16(Bt[n][k], At[m][k], acc[ai][bj][m][n], 0, 0, 0); __builtin_amdgcn_s_setprio(0); } while (0)
; #define PG8_WAIT_V(n) asm volatile("s_waitcnt vmcnt(" #n ")" ::: "memory")
; #define PG8_WAIT_L(n) asm volatile("s_waitcnt lgkmcnt(" #n ")" ::: "memory")
; #define PG8_BAR __builtin_amdgcn_s_barrier()
; #define PG8_SCHED __builtin_amdgcn_sched_barrier(0)
; template <class Epi, class Sched>
; __device__ __forceinline__ void gemm_phase(LAS unsigned char* lds, const int K, const Sched& S, const Epi& E) {
;     ...
;             PG8_BAR; PG8_WAIT_L(0); PG8_MMA(1, 0, At, B0); PG8_BAR; PG8_SCHED;
;             PG8_STAGE(PG8_SB(1, 1), b3 + hstep, voffB);
;             PG8_WAIT_V(6); PG8_BAR; PG8_MMA(1, 1, At, B1); PG8_BAR;
;         }
;         if constexpr (!Epi::AFTER_DRAIN) E(acc, cur, wr, wc, fr, fq);
;     __device__ __forceinline__ void operator()(const f32x4 (&acc)[2][2][4][2], const Unit& u, int wr, int wc, int fr, int fq) const {
;         bf16_t* base = (bf16_t*)u.po + (size_t)wr * u.RS + (size_t)fr * u.rp + (size_t)(wc >> 1) * u.CS + (wc & 1) * 32 + 8 * fq;
; #pragma unroll
;         for (int ai = 0; ai < 2; ++ai)
; #pragma unroll
;             for (int m = 0; m < 4; ++m) { bf16_t* rowp = base + (size_t)(2 * ai) * u.RS + (size_t)(m * 16) * u.rp;
; #pragma unroll
;                 for (int bj = 0; bj < 2; ++bj) { const f32x4 v0 = acc[ai][bj][m][0], v1 = acc[ai][bj][m][1];
;                     u32x4 w; w.x = cvt_pk_bf16(v0[0], v0[1]); w.y = cvt_pk_bf16(v0[2], v0[3]); w.z = cvt_pk_bf16(v1[0], v1[1]); w.w = cvt_pk_bf16(v1[2], v1[3]);
;                     *(u32x4*)(rowp + (size_t)(2 * bj) * u.CS) = w; } }
	s_waitcnt lgkmcnt(0)
	s_setprio 1
	s_waitcnt lgkmcnt(0)
	v_mfma_f32_16x16x32_bf16 v[60:63], v[156:159], v[178:181], v[60:63]
	v_mfma_f32_16x16x32_bf16 v[56:59], v[164:167], v[178:181], v[56:59]
	v_mfma_f32_16x16x32_bf16 v[52:55], v[156:159], v[186:189], v[52:55]
	v_mfma_f32_16x16x32_bf16 v[44:47], v[164:167], v[186:189], v[44:47]
	v_mfma_f32_16x16x32_bf16 v[36:39], v[156:159], v[194:197], v[36:39]
	v_mfma_f32_16x16x32_bf16 v[28:31], v[164:167], v[194:197], v[28:31]
	v_mfma_f32_16x16x32_bf16 v[20:23], v[156:159], v[202:205], v[20:23]
	v_mfma_f32_16x16x32_bf16 v[12:15], v[164:167], v[202:205], v[12:15]
	v_mfma_f32_16x16x32_bf16 v[60:63], v[160:163], v[182:185], v[60:63]
	v_mfma_f32_16x16x32_bf16 v[56:59], v[174:177], v[182:185], v[56:59]
	v_mfma_f32_16x16x32_bf16 v[52:55], v[160:163], v[190:193], v[52:55]
	v_mfma_f32_16x16x32_bf16 v[44:47], v[174:177], v[190:193], v[44:47]
	v_mfma_f32_16x16x32_bf16 v[36:39], v[160:163], v[198:201], v[36:39]
	v_mfma_f32_16x16x32_bf16 v[28:31], v[174:177], v[198:201], v[28:31]
	v_mfma_f32_16x16x32_bf16 v[20:23], v[160:163], v[206:209], v[20:23]
	v_mfma_f32_16x16x32_bf16 v[12:15], v[174:177], v[206:209], v[12:15]
	s_setprio 0
	s_barrier
	s_add_u32 s66, s66, 0x40080
	s_addc_u32 s67, s67, 0
	s_add_i32 s68, s68, s53
	v_lshl_add_u64 v[150:151], s[66:67], 0, v[136:137]
	s_mov_b32 m0, s68
	s_nop 0
	global_load_lds_dwordx4 v[150:151], off
	v_lshl_add_u64 v[150:151], s[66:67], 0, v[140:141]
	s_add_i32 m0, s68, 0x2000
	s_nop 0
	global_load_lds_dwordx4 v[150:151], off
	s_waitcnt vmcnt(6)
	s_barrier
	s_setprio 1
	v_mfma_f32_16x16x32_bf16 v[48:51], v[210:213], v[178:181], v[48:51]
	v_mfma_f32_16x16x32_bf16 v[40:43], v[218:221], v[178:181], v[40:43]
	v_mfma_f32_16x16x32_bf16 v[32:35], v[210:213], v[186:189], v[32:35]
	v_mfma_f32_16x16x32_bf16 v[24:27], v[218:221], v[186:189], v[24:27]
	v_mfma_f32_16x16x32_bf16 v[16:19], v[210:213], v[194:197], v[16:19]
	v_mfma_f32_16x16x32_bf16 v[8:11], v[218:221], v[194:197], v[8:11]
	v_mfma_f32_16x16x32_bf16 v[4:7], v[210:213], v[202:205], v[4:7]
	v_mfma_f32_16x16x32_bf16 v[0:3], v[218:221], v[202:205], v[0:3]
	v_mfma_f32_16x16x32_bf16 v[48:51], v[214:217], v[182:185], v[48:51]
	v_mfma_f32_16x16x32_bf16 v[40:43], v[222:225], v[182:185], v[40:43]
	v_mfma_f32_16x16x32_bf16 v[32:35], v[214:217], v[190:193], v[32:35]
	v_mfma_f32_16x16x32_bf16 v[24:27], v[222:225], v[190:193], v[24:27]
	v_mfma_f32_16x16x32_bf16 v[16:19], v[214:217], v[198:201], v[16:19]
	v_mfma_f32_16x16x32_bf16 v[8:11], v[222:225], v[198:201], v[8:11]
	v_mfma_f32_16x16x32_bf16 v[4:7], v[214:217], v[206:209], v[4:7]
	v_mfma_f32_16x16x32_bf16 v[0:3], v[222:225], v[206:209], v[0:3]
	s_setprio 0
	s_add_i32 s83, s83, 2
	s_add_u32 s64, s64, 0x100
	s_addc_u32 s65, s65, 0
	s_add_u32 s41, s41, 0x100
	s_addc_u32 s82, s82, 0
	s_cmp_gt_u32 s83, 13
	s_barrier
	s_cbranch_scc0 .LBB0_299
	s_add_u32 s62, s62, s38
	s_addc_u32 s63, s63, s39
	v_lshl_add_u64 v[150:151], s[62:63], 0, v[142:143]
	v_lshl_add_u64 v[150:151], v[150:151], 0, s[0:1]
	s_mov_b32 s41, s1
	v_lshl_add_u64 v[150:151], v[150:151], 0, s[40:41]
	v_mov_b32_e32 v149, v143
	v_lshl_add_u64 v[150:151], v[150:151], 0, v[148:149]
	v_cvt_pk_bf16_f32 v124, v124, v125
	v_cvt_pk_bf16_f32 v125, v126, v127
	v_cvt_pk_bf16_f32 v126, v120, v121
	v_cvt_pk_bf16_f32 v127, v122, v123
	global_store_dwordx4 v[150:151], v[124:127], off sc1
	v_cvt_pk_bf16_f32 v112, v112, v113
	v_cvt_pk_bf16_f32 v113, v114, v115
	v_cvt_pk_bf16_f32 v114, v104, v105
	v_cvt_pk_bf16_f32 v115, v106, v107
	global_store_dwordx4 v[150:151], v[112:115], off offset:256 sc1
	v_cvt_pk_bf16_f32 v104, v116, v117
	v_cvt_pk_bf16_f32 v105, v118, v119
	v_cvt_pk_bf16_f32 v106, v108, v109
	v_add_co_u32_e32 v108, vcc, s74, v150
	v_cvt_pk_bf16_f32 v107, v110, v111
	s_mov_b64 s[62:63], s[48:49]
	s_nop 0
	v_addc_co_u32_e32 v109, vcc, 0, v151, vcc
	global_store_dwordx4 v[108:109], v[104:107], off sc1
	v_cvt_pk_bf16_f32 v96, v96, v97
	v_cvt_pk_bf16_f32 v97, v98, v99
	v_cvt_pk_bf16_f32 v98, v88, v89
	v_cvt_pk_bf16_f32 v99, v90, v91
	global_store_dwordx4 v[108:109], v[96:99], off offset:256 sc1
	v_cvt_pk_bf16_f32 v88, v100, v101
	v_cvt_pk_bf16_f32 v89, v102, v103
	v_cvt_pk_bf16_f32 v90, v92, v93
	v_add_co_u32_e32 v92, vcc, s75, v150
	v_cvt_pk_bf16_f32 v91, v94, v95
	s_mov_b64 s[66:67], s[46:47]
	s_nop 0
	v_addc_co_u32_e32 v93, vcc, 0, v151, vcc
	global_store_dwordx4 v[92:93], v[88:91], off sc1
	v_cvt_pk_bf16_f32 v80, v80, v81
	v_cvt_pk_bf16_f32 v81, v82, v83
	v_cvt_pk_bf16_f32 v82, v72, v73
	v_cvt_pk_bf16_f32 v83, v74, v75
	global_store_dwordx4 v[92:93], v[80:83], off offset:256 sc1
	v_cvt_pk_bf16_f32 v72, v84, v85
	v_cvt_pk_bf16_f32 v73, v86, v87
	v_cvt_pk_bf16_f32 v74, v76, v77
	v_add_co_u32_e32 v76, vcc, s76, v150
	v_cvt_pk_bf16_f32 v75, v78, v79
	s_mov_b64 s[64:65], s[44:45]
	s_nop 0
	v_addc_co_u32_e32 v77, vcc, 0, v151, vcc
	global_store_dwordx4 v[76:77], v[72:75], off sc1
	v_cvt_pk_bf16_f32 v68, v68, v69
	v_cvt_pk_bf16_f32 v69, v70, v71
	v_cvt_pk_bf16_f32 v70, v64, v65
	v_cvt_pk_bf16_f32 v71, v66, v67
	global_store_dwordx4 v[76:77], v[68:71], off offset:256 sc1
	v_cvt_pk_bf16_f32 v60, v60, v61
	v_cvt_pk_bf16_f32 v61, v62, v63
	v_cvt_pk_bf16_f32 v62, v56, v57
	v_add_co_u32_e32 v56, vcc, s77, v150
	v_cvt_pk_bf16_f32 v63, v58, v59
	s_nop 1
	v_addc_co_u32_e32 v57, vcc, 0, v151, vcc
	global_store_dwordx4 v[56:57], v[60:63], off sc1
	v_cvt_pk_bf16_f32 v48, v48, v49
	v_cvt_pk_bf16_f32 v49, v50, v51
	v_cvt_pk_bf16_f32 v50, v40, v41
	v_cvt_pk_bf16_f32 v51, v42, v43
	global_store_dwordx4 v[56:57], v[48:51], off offset:256 sc1
	v_cvt_pk_bf16_f32 v40, v52, v53
	v_cvt_pk_bf16_f32 v41, v54, v55
	v_cvt_pk_bf16_f32 v42, v44, v45
	v_add_co_u32_e32 v44, vcc, s78, v150
	v_cvt_pk_bf16_f32 v43, v46, v47
	s_nop 1
	v_addc_co_u32_e32 v45, vcc, 0, v151, vcc
	global_store_dwordx4 v[44:45], v[40:43], off sc1
	v_cvt_pk_bf16_f32 v32, v32, v33
	v_cvt_pk_bf16_f32 v33, v34, v35
	v_cvt_pk_bf16_f32 v34, v24, v25
	v_cvt_pk_bf16_f32 v35, v26, v27
	global_store_dwordx4 v[44:45], v[32:35], off offset:256 sc1
	v_cvt_pk_bf16_f32 v24, v36, v37
	v_cvt_pk_bf16_f32 v25, v38, v39
	v_cvt_pk_bf16_f32 v26, v28, v29
	v_add_co_u32_e32 v28, vcc, s79, v150
	v_cvt_pk_bf16_f32 v27, v30, v31
	s_nop 1
	v_addc_co_u32_e32 v29, vcc, 0, v151, vcc
	global_store_dwordx4 v[28:29], v[24:27], off sc1
	v_cvt_pk_bf16_f32 v16, v16, v17
	v_cvt_pk_bf16_f32 v17, v18, v19
	v_cvt_pk_bf16_f32 v18, v8, v9
	v_cvt_pk_bf16_f32 v19, v10, v11
	global_store_dwordx4 v[28:29], v[16:19], off offset:256 sc1
	v_cvt_pk_bf16_f32 v8, v20, v21
	v_cvt_pk_bf16_f32 v9, v22, v23
	v_cvt_pk_bf16_f32 v10, v12, v13
	v_add_co_u32_e32 v12, vcc, s80, v150
	v_cvt_pk_bf16_f32 v11, v14, v15
	s_nop 1
	v_addc_co_u32_e32 v13, vcc, 0, v151, vcc
	s_and_b64 vcc, exec, s[42:43]
	global_store_dwordx4 v[12:13], v[8:11], off sc1
	v_cvt_pk_bf16_f32 v4, v4, v5
	v_cvt_pk_bf16_f32 v5, v6, v7
	v_cvt_pk_bf16_f32 v6, v0, v1
	v_cvt_pk_bf16_f32 v7, v2, v3
	global_store_dwordx4 v[12:13], v[4:7], off offset:256 sc1
	s_cbranch_vccz .LBB0_292
	s_waitcnt vmcnt(0)
	s_cmpk_gt_u32 s5, 0xff
	s_cbranch_scc1 .LBB0_303
	s_barrier

; __device__ __forceinline__ unsigned cvt_pk_bf16(float lo, float hi) { unsigned r; asm volatile("v_cvt_pk_bf16_f32 %0, %1, %2" : "=v"(r) : "v"(lo), "v"(hi)); return r; }
; __device__ __forceinline__ float bf_lo(unsigned w) { return __uint_as_float(w << 16); }
; __device__ __forceinline__ float bf_hi(unsigned w) { return __uint_as_float(w & 0xffff0000u); }
; __device__ __forceinline__ void combine_row(int row, const float (&y)[8], const float* SSQNA, bf16_t* YCAT, int lane) {
;     float s = 0.f;
; #pragma unroll
;     for (int j = 0; j < 8; ++j) s += y[j] * y[j];
;     s = wave_sum(s);
;     const float rstd = 1.0f / sqrtf(s * (1.0f / 512.0f) + EPS);
;     u32x4 o; o.x = cvt_pk_bf16(y[0] * rstd, y[1] * rstd); o.y = cvt_pk_bf16(y[2] * rstd, y[3] * rstd); o.z = cvt_pk_bf16(y[4] * rstd, y[5] * rstd); o.w = cvt_pk_bf16(y[6] * rstd, y[7] * rstd);
;     *(u32x4*)(YCAT + (size_t)row * DM + lane * 8) = o;
;     float t = SSQNA[(size_t)row * 8 + (lane & 7)]; t += __shfl_xor(t, 1); t += __shfl_xor(t, 2); t += __shfl_xor(t, 4);
;     const float rn = 1.0f / sqrtf(t * (1.0f / 512.0f) + EPS);
;     u32x4* ap = (u32x4*)(YCAT + (size_t)row * DM + 512 + lane * 8); const u32x4 aw = *ap; u32x4 ow;
; #pragma unroll
;     for (int j = 0; j < 4; ++j) ow[j] = cvt_pk_bf16(bf_lo(aw[j]) * rn, bf_hi(aw[j]) * rn);
;     *ap = ow;
; }
.LBB0_405:
	s_or_b64 exec, exec, s[6:7]
	v_pk_add_f32 v[0:1], v[20:21], v[28:29] neg_lo:[0,1] neg_hi:[0,1]
	v_pk_add_f32 v[2:3], v[22:23], v[30:31] neg_lo:[0,1] neg_hi:[0,1]
	v_pk_mul_f32 v[20:21], v[0:1], v[0:1]
	v_pk_mul_f32 v[22:23], v[2:3], v[2:3]
	v_add_f32_e32 v10, v20, v21
	v_pk_add_f32 v[4:5], v[24:25], v[32:33] neg_lo:[0,1] neg_hi:[0,1]
	v_add_f32_e32 v10, v22, v10
	v_pk_mul_f32 v[24:25], v[4:5], v[4:5]
	v_add_f32_e32 v10, v23, v10
	v_pk_add_f32 v[6:7], v[26:27], v[34:35] neg_lo:[0,1] neg_hi:[0,1]
	v_add_f32_e32 v10, v24, v10
	v_pk_mul_f32 v[26:27], v[6:7], v[6:7]
	v_add_f32_e32 v10, v25, v10
	v_add_f32_e32 v10, v26, v10
	v_add_f32_e32 v10, v27, v10
	ds_bpermute_b32 v20, v47, v10
	v_lshlrev_b32_e32 v24, 11, v59
	s_add_i32 s10, s10, s11
	s_waitcnt lgkmcnt(0)
	v_add_f32_e32 v10, v10, v20
	ds_bpermute_b32 v20, v48, v10
	s_waitcnt lgkmcnt(0)
	v_add_f32_e32 v10, v10, v20
	ds_bpermute_b32 v20, v49, v10
	s_waitcnt lgkmcnt(0)
	v_add_f32_e32 v10, v10, v20
	ds_bpermute_b32 v20, v50, v10
	s_waitcnt lgkmcnt(0)
	v_add_f32_e32 v10, v10, v20
	ds_bpermute_b32 v20, v51, v10
	s_waitcnt lgkmcnt(0)
	v_add_f32_e32 v10, v10, v20
	ds_bpermute_b32 v20, v52, v10
	s_waitcnt lgkmcnt(0)
	v_add_f32_e32 v10, v10, v20
	v_fmamk_f32 v10, v10, 0x3b000000, v55
	v_mul_f32_e32 v20, 0x4f800000, v10
	v_cmp_gt_f32_e32 vcc, s33, v10
	s_nop 1
	v_cndmask_b32_e32 v10, v10, v20, vcc
	v_sqrt_f32_e32 v22, v10
	v_or_b32_e32 v20, v24, v58
	v_ashrrev_i32_e32 v21, 31, v20
	v_add_u32_e32 v23, -1, v22
	v_add_u32_e32 v25, 1, v22
	v_fma_f32 v26, -v23, v22, v10
	v_fma_f32 v27, -v25, v22, v10
	v_cmp_ge_f32_e64 s[6:7], 0, v26
	s_nop 1
	v_cndmask_b32_e64 v22, v22, v23, s[6:7]
	v_cmp_lt_f32_e64 s[6:7], 0, v27
	s_nop 1
	v_cndmask_b32_e64 v22, v22, v25, s[6:7]
	v_mul_f32_e32 v23, 0x37800000, v22
	v_cndmask_b32_e32 v22, v22, v23, vcc
	v_cmp_class_f32_e32 vcc, v10, v56
	s_nop 1
	v_cndmask_b32_e32 v10, v22, v10, vcc
	v_div_scale_f32 v25, s[6:7], v10, v10, 1.0
	v_rcp_f32_e32 v26, v25
	v_div_scale_f32 v27, vcc, 1.0, v10, 1.0
	v_lshlrev_b64 v[22:23], 11, v[20:21]
	v_fma_f32 v28, -v25, v26, 1.0
	v_fmac_f32_e32 v26, v28, v26
	v_mul_f32_e32 v28, v27, v26
	v_fma_f32 v29, -v25, v28, v27
	v_fmac_f32_e32 v28, v29, v26
	v_fma_f32 v25, -v25, v28, v27
	v_div_fmas_f32 v25, v25, v26, v28
	v_div_fixup_f32 v10, v25, v10, 1.0
	v_mul_f32_e32 v0, v0, v10
	v_mul_f32_e32 v1, v1, v10
	v_mul_f32_e32 v2, v2, v10
	v_mul_f32_e32 v4, v4, v10
	v_mul_f32_e32 v5, v5, v10
	v_mul_f32_e32 v3, v3, v10
	v_cvt_pk_bf16_f32 v0, v0, v1
	v_cvt_pk_bf16_f32 v1, v2, v3
	v_cvt_pk_bf16_f32 v2, v4, v5
	v_lshl_add_u64 v[4:5], v[16:17], 0, v[22:23]
	v_mul_f32_e32 v6, v6, v10
	v_mul_f32_e32 v7, v7, v10
	v_cvt_pk_bf16_f32 v3, v6, v7
	global_store_dwordx4 v[4:5], v[0:3], off sc1
	v_mul_f32_e32 v6, v43, v43
	v_fmac_f32_e32 v6, v42, v42
	v_lshlrev_b64 v[0:1], 5, v[20:21]
	v_lshl_add_u64 v[0:1], v[14:15], 0, v[0:1]
	global_load_dword v7, v[0:1], off
	v_fmac_f32_e32 v6, v40, v40
	v_fmac_f32_e32 v6, v41, v41
	v_fmac_f32_e32 v6, v38, v38
	v_fmac_f32_e32 v6, v39, v39
	v_fmac_f32_e32 v6, v36, v36
	v_fmac_f32_e32 v6, v37, v37
	ds_bpermute_b32 v10, v47, v6
	global_load_dwordx4 v[0:3], v[4:5], off offset:1024
	s_waitcnt lgkmcnt(0)
	v_add_f32_e32 v6, v6, v10
	ds_bpermute_b32 v10, v48, v6
	s_waitcnt lgkmcnt(0)
	v_add_f32_e32 v6, v6, v10
	ds_bpermute_b32 v10, v49, v6
	s_waitcnt lgkmcnt(0)
	v_add_f32_e32 v6, v6, v10
	ds_bpermute_b32 v10, v50, v6
	s_waitcnt lgkmcnt(0)
	v_add_f32_e32 v6, v6, v10
	ds_bpermute_b32 v10, v51, v6
	s_waitcnt lgkmcnt(0)
	v_add_f32_e32 v6, v6, v10
	ds_bpermute_b32 v10, v52, v6
	s_waitcnt lgkmcnt(0)
	v_add_f32_e32 v6, v6, v10
	v_fmamk_f32 v6, v6, 0x3b000000, v55
	v_mul_f32_e32 v10, 0x4f800000, v6
	v_cmp_gt_f32_e32 vcc, s33, v6
	s_waitcnt vmcnt(0)
	v_lshlrev_b32_e32 v26, 16, v2
	v_cndmask_b32_e32 v10, v6, v10, vcc
	v_sqrt_f32_e32 v20, v10
	v_sub_u32_e32 v6, 0x800, v58
	v_cndmask_b32_e64 v6, v6, v57, s[4:5]
	v_add_u32_e32 v6, v6, v24
	v_add_u32_e32 v21, -1, v20
	v_add_u32_e32 v22, 1, v20
	v_fma_f32 v23, -v21, v20, v10
	v_fma_f32 v24, -v22, v20, v10
	v_cmp_ge_f32_e64 s[4:5], 0, v23
	v_and_b32_e32 v2, 0xffff0000, v2
	v_lshlrev_b32_e32 v27, 16, v3
	v_cndmask_b32_e64 v20, v20, v21, s[4:5]
	v_cmp_lt_f32_e64 s[4:5], 0, v24
	v_and_b32_e32 v3, 0xffff0000, v3
	s_nop 0
	v_cndmask_b32_e64 v20, v20, v22, s[4:5]
	ds_bpermute_b32 v22, v47, v7
	v_mul_f32_e32 v21, 0x37800000, v20
	v_cndmask_b32_e32 v20, v20, v21, vcc
	v_cmp_class_f32_e32 vcc, v10, v56
	s_waitcnt lgkmcnt(0)
	v_add_f32_e32 v7, v7, v22
	ds_bpermute_b32 v22, v48, v7
	v_cndmask_b32_e32 v10, v20, v10, vcc
	v_div_scale_f32 v20, s[4:5], v10, v10, 1.0
	v_rcp_f32_e32 v21, v20
	s_waitcnt lgkmcnt(0)
; __device__ __forceinline__ unsigned cvt_pk_bf16(float lo, float hi) { unsigned r; asm volatile("v_cvt_pk_bf16_f32 %0, %1, %2" : "=v"(r) : "v"(lo), "v"(hi)); return r; }
; __device__ __forceinline__ float bf_lo(unsigned w) { return __uint_as_float(w << 16); }
; __device__ __forceinline__ float bf_hi(unsigned w) { return __uint_as_float(w & 0xffff0000u); }
; __device__ __forceinline__ void combine_row(int row, const float (&y)[8], const float* SSQNA, bf16_t* YCAT, int lane) {
;     ...
;     float t = SSQNA[(size_t)row * 8 + (lane & 7)]; t += __shfl_xor(t, 1); t += __shfl_xor(t, 2); t += __shfl_xor(t, 4);
;     const float rn = 1.0f / sqrtf(t * (1.0f / 512.0f) + EPS);
;     u32x4* ap = (u32x4*)(YCAT + (size_t)row * DM + 512 + lane * 8); const u32x4 aw = *ap; u32x4 ow;
; #pragma unroll
;     for (int j = 0; j < 4; ++j) ow[j] = cvt_pk_bf16(bf_lo(aw[j]) * rn, bf_hi(aw[j]) * rn);
;     *ap = ow;
; }
; __device__ __forceinline__ void pass_combine(const bf16_t* PQ, const float* SP, const float* XM, const float* SSQNA, bf16_t* YCAT) {
;     ...
;         combine_row(b * SEQ + kk, y1, SSQNA, YCAT, lane);
;         combine_row(b * SEQ + (kk == 0 ? 1024 : SEQ - kk), y2, SSQNA, YCAT, lane);
	v_add_f32_e32 v7, v7, v22
	ds_bpermute_b32 v22, v49, v7
	v_div_scale_f32 v23, s[4:5], 1.0, v10, 1.0
	v_fma_f32 v24, -v20, v21, 1.0
	v_fmac_f32_e32 v21, v24, v21
	s_waitcnt lgkmcnt(0)
	v_add_f32_e32 v7, v7, v22
	v_fmamk_f32 v7, v7, 0x3b000000, v55
	v_mul_f32_e32 v22, 0x4f800000, v7
	v_cmp_gt_f32_e32 vcc, s33, v7
	v_mul_f32_e32 v24, v23, v21
	v_fma_f32 v25, -v20, v24, v23
	v_cndmask_b32_e32 v7, v7, v22, vcc
	v_sqrt_f32_e32 v22, v7
	v_fmac_f32_e32 v24, v25, v21
	v_fma_f32 v20, -v20, v24, v23
	v_lshlrev_b32_e32 v23, 16, v0
	v_add_u32_e32 v28, -1, v22
	v_add_u32_e32 v29, 1, v22
	v_fma_f32 v30, -v28, v22, v7
	v_fma_f32 v31, -v29, v22, v7
	v_cmp_ge_f32_e64 s[6:7], 0, v30
	v_and_b32_e32 v0, 0xffff0000, v0
	v_lshlrev_b32_e32 v25, 16, v1
	v_cndmask_b32_e64 v22, v22, v28, s[6:7]
	v_cmp_lt_f32_e64 s[6:7], 0, v31
	v_and_b32_e32 v1, 0xffff0000, v1
	s_nop 0
	v_cndmask_b32_e64 v22, v22, v29, s[6:7]
	v_mul_f32_e32 v28, 0x37800000, v22
	v_cndmask_b32_e32 v22, v22, v28, vcc
	v_cmp_class_f32_e32 vcc, v7, v56
	s_nop 1
	v_cndmask_b32_e32 v7, v22, v7, vcc
	v_div_scale_f32 v22, s[6:7], v7, v7, 1.0
	v_rcp_f32_e32 v28, v22
	v_div_scale_f32 v29, vcc, 1.0, v7, 1.0
	v_fma_f32 v30, -v22, v28, 1.0
	v_fmac_f32_e32 v28, v30, v28
	v_mul_f32_e32 v30, v29, v28
	v_fma_f32 v31, -v22, v30, v29
	v_fmac_f32_e32 v30, v31, v28
	v_fma_f32 v22, -v22, v30, v29
	v_div_fmas_f32 v22, v22, v28, v30
	s_mov_b64 vcc, s[4:5]
	v_div_fixup_f32 v7, v22, v7, 1.0
	v_div_fmas_f32 v20, v20, v21, v24
	v_mul_f32_e32 v21, v7, v23
	v_mul_f32_e32 v0, v7, v0
	v_mul_f32_e32 v22, v7, v25
	v_mul_f32_e32 v1, v7, v1
	v_mul_f32_e32 v23, v7, v26
	v_mul_f32_e32 v2, v7, v2
	v_mul_f32_e32 v24, v7, v27
	v_mul_f32_e32 v3, v7, v3
	v_div_fixup_f32 v7, v20, v10, 1.0
	v_cvt_pk_bf16_f32 v0, v21, v0
	v_cvt_pk_bf16_f32 v1, v22, v1
	v_cvt_pk_bf16_f32 v2, v23, v2
	v_cvt_pk_bf16_f32 v3, v24, v3
	v_mul_f32_e32 v10, v42, v7
	v_mul_f32_e32 v20, v43, v7
	v_mul_f32_e32 v21, v40, v7
	v_mul_f32_e32 v22, v41, v7
	v_mul_f32_e32 v23, v38, v7
	v_mul_f32_e32 v24, v39, v7
	v_mul_f32_e32 v25, v36, v7
	v_mul_f32_e32 v7, v37, v7
	global_store_dwordx4 v[4:5], v[0:3], off offset:1024 sc1
	s_nop 1
	v_cvt_pk_bf16_f32 v0, v10, v20
	v_cvt_pk_bf16_f32 v1, v21, v22
	v_cvt_pk_bf16_f32 v2, v23, v24
	v_cvt_pk_bf16_f32 v3, v25, v7
	v_ashrrev_i32_e32 v7, 31, v6
	v_lshlrev_b64 v[4:5], 11, v[6:7]
	v_lshl_add_u64 v[4:5], v[16:17], 0, v[4:5]
	global_store_dwordx4 v[4:5], v[0:3], off sc1
	v_add_u32_e32 v10, s10, v9
	v_cmp_lt_i32_e64 s[4:5], s38, v10
	v_lshlrev_b64 v[0:1], 5, v[6:7]
	v_lshl_add_u64 v[0:1], v[14:15], 0, v[0:1]
	global_load_dword v6, v[0:1], off
	s_nop 0
	global_load_dwordx4 v[0:3], v[4:5], off offset:1024
	s_or_b64 s[20:21], s[4:5], s[20:21]
	s_waitcnt vmcnt(1)
	ds_bpermute_b32 v7, v47, v6
	s_waitcnt vmcnt(0)
	v_lshlrev_b32_e32 v10, 16, v0
	v_and_b32_e32 v0, 0xffff0000, v0
	v_lshlrev_b32_e32 v20, 16, v1
	v_and_b32_e32 v1, 0xffff0000, v1
	s_waitcnt lgkmcnt(0)
	v_add_f32_e32 v6, v6, v7
	ds_bpermute_b32 v7, v48, v6
	v_lshlrev_b32_e32 v21, 16, v2
	v_and_b32_e32 v2, 0xffff0000, v2
	v_lshlrev_b32_e32 v22, 16, v3
	v_and_b32_e32 v3, 0xffff0000, v3
	s_waitcnt lgkmcnt(0)
	v_add_f32_e32 v6, v6, v7
	ds_bpermute_b32 v7, v49, v6
	s_waitcnt lgkmcnt(0)
	v_add_f32_e32 v6, v6, v7
	v_fmamk_f32 v6, v6, 0x3b000000, v55
	v_mul_f32_e32 v7, 0x4f800000, v6
	v_cmp_gt_f32_e32 vcc, s33, v6
	s_nop 1
	v_cndmask_b32_e32 v6, v6, v7, vcc
	v_sqrt_f32_e32 v7, v6
	s_nop 0
	v_add_u32_e32 v23, -1, v7
	v_add_u32_e32 v24, 1, v7
	v_fma_f32 v25, -v23, v7, v6
	v_fma_f32 v26, -v24, v7, v6
	v_cmp_ge_f32_e64 s[6:7], 0, v25
	s_nop 1
	v_cndmask_b32_e64 v7, v7, v23, s[6:7]
	v_cmp_lt_f32_e64 s[6:7], 0, v26
	s_nop 1
	v_cndmask_b32_e64 v7, v7, v24, s[6:7]
	v_mul_f32_e32 v23, 0x37800000, v7
	v_cndmask_b32_e32 v7, v7, v23, vcc
	v_cmp_class_f32_e32 vcc, v6, v56
	s_nop 1
	v_cndmask_b32_e32 v6, v7, v6, vcc
	v_div_scale_f32 v7, s[6:7], v6, v6, 1.0
	v_rcp_f32_e32 v23, v7
	v_div_scale_f32 v24, vcc, 1.0, v6, 1.0
	v_fma_f32 v25, -v7, v23, 1.0
	v_fmac_f32_e32 v23, v25, v23
	v_mul_f32_e32 v25, v24, v23
	v_fma_f32 v26, -v7, v25, v24
	v_fmac_f32_e32 v25, v26, v23
	v_fma_f32 v7, -v7, v25, v24
	v_div_fmas_f32 v7, v7, v23, v25
	v_div_fixup_f32 v6, v7, v6, 1.0
	v_mul_f32_e32 v0, v6, v0
	v_mul_f32_e32 v1, v6, v1
	v_mul_f32_e32 v2, v6, v2
	v_mul_f32_e32 v3, v6, v3
	v_mul_f32_e32 v7, v6, v10
	v_mul_f32_e32 v10, v6, v20
	v_mul_f32_e32 v20, v6, v21
	v_mul_f32_e32 v21, v6, v22
	v_cvt_pk_bf16_f32 v0, v7, v0
	v_cvt_pk_bf16_f32 v1, v10, v1
	v_cvt_pk_bf16_f32 v2, v20, v2
	v_cvt_pk_bf16_f32 v3, v21, v3
	global_store_dwordx4 v[4:5], v[0:3], off offset:1024 sc1
	s_andn2_b64 exec, exec, s[20:21]
	s_cbranch_execz .LBB0_411

; __device__ __forceinline__ unsigned cvt_pk_bf16(float lo, float hi) { unsigned r; asm volatile("v_cvt_pk_bf16_f32 %0, %1, %2" : "=v"(r) : "v"(lo), "v"(hi)); return r; }
;     __device__ __forceinline__ void operator()(f32x4 (&acc)[2][2][4][2], const Unit& u, int wr, int wc, int fr, int fq) const {
;     ...
;         if (f0 || f15) {
; #pragma unroll
;             for (int bj = 0; bj < 2; ++bj)
; #pragma unroll
;                 for (int q = 0; q < 2; ++q) { const f32x4 a0 = f0 ? acc[0][bj][q][0] : acc[1][bj][2 + q][0], a1 = f0 ? acc[0][bj][q][1] : acc[1][bj][2 + q][1];
;                     u32x4 w; w.x = cvt_pk_bf16(a0[0], a0[1]); w.y = cvt_pk_bf16(a0[2], a0[3]); w.z = cvt_pk_bf16(a1[0], a1[1]); w.w = cvt_pk_bf16(a1[2], a1[3]);
;                     *(u32x4*)(side + (size_t)(sc * 4 + (f0 ? q : 2 + q)) * (2 * DFF) + bj * DFF + J0) = w; }
;         }
; #pragma unroll
;         for (int bj = 0; bj < 2; ++bj)
; #pragma unroll
;             for (int n = 0; n < 2; ++n) {
;                 const int col = bj * DFF + J0 + n * 4;
;                 const float csc = bj ? 0.6931471805599453f : 1.4426950408889634f;
;                 const f32x4 k0 = *(const f32x4*)(cw + col) * csc, k1 = *(const f32x4*)(cw + 2 * DFF + col) * csc, k2 = *(const f32x4*)(cw + 4 * DFF + col) * csc, kb = *(const f32x4*)(cb + col) * csc;
;                 const f32x4 a0 = acc[0][bj][0][n], a1 = acc[0][bj][1][n], a2 = acc[0][bj][2][n], a3 = acc[0][bj][3][n];
;                 const f32x4 b0 = acc[1][bj][0][n], b1 = acc[1][bj][1][n], b2 = acc[1][bj][2][n], b3 = acc[1][bj][3][n];
;                 f32x4 pa, pb, na, nb;
; #pragma unroll
;                 for (int j = 0; j < 4; ++j) {
;                     const float t = dpp_f<0x121>(a3[j]);
;                     const float s1 = dpp_f<0x111>(b3[j]);
;                     const float un = dpp_f<0x12F>(b0[j]);
;                     const float s0 = dpp_f<0x101>(a0[j]);
;                     pa[j] = t; pb[j] = f0 ? t : s1; na[j] = f15 ? un : s0; nb[j] = un; }
.LBB0_805:
	s_or_b64 exec, exec, s[68:69]
	s_lshl_b32 s10, s66, 1
	s_add_i32 s10, s10, s77
	v_ashrrev_i32_e32 v151, 31, v150
	s_and_saveexec_b64 s[12:13], s[70:71]
	s_cbranch_execz .LBB0_807
	s_lshl_b32 s11, s10, 2
	v_cndmask_b32_e64 v129, v102, v86, s[8:9]
	v_cndmask_b32_e64 v130, v103, v87, s[8:9]
	v_cndmask_b32_e64 v128, v100, v84, s[8:9]
	v_cndmask_b32_e64 v131, v101, v85, s[8:9]
	v_cndmask_b32_e64 v132, v66, v78, s[8:9]
	v_cndmask_b32_e64 v133, v67, v79, s[8:9]
	v_cndmask_b32_e64 v134, v64, v76, s[8:9]
	v_cndmask_b32_e64 v135, v65, v77, s[8:9]
	v_cvt_pk_bf16_f32 v128, v128, v131
	v_cvt_pk_bf16_f32 v129, v129, v130
	v_cvt_pk_bf16_f32 v130, v134, v135
	v_cvt_pk_bf16_f32 v131, v132, v133
	v_or_b32_e32 v134, s11, v153
	v_mov_b64_e32 v[132:133], s[20:21]
	v_mad_i64_i32 v[134:135], s[52:53], v134, s90, v[132:133]
	v_lshlrev_b64 v[148:149], 1, v[150:151]
	v_lshl_add_u64 v[134:135], v[134:135], 0, v[148:149]
	global_store_dwordx4 v[134:135], v[128:131], off sc1
	v_cndmask_b32_e64 v161, v70, v74, s[8:9]
	v_cndmask_b32_e64 v162, v71, v75, s[8:9]
	v_cndmask_b32_e64 v129, v110, v126, s[8:9]
	v_cndmask_b32_e64 v130, v111, v127, s[8:9]
	v_cndmask_b32_e64 v128, v108, v124, s[8:9]
	v_cndmask_b32_e64 v131, v109, v125, s[8:9]
	v_cndmask_b32_e64 v163, v68, v72, s[8:9]
	v_cndmask_b32_e64 v164, v69, v73, s[8:9]
	v_cvt_pk_bf16_f32 v128, v128, v131
	v_cvt_pk_bf16_f32 v129, v129, v130
	v_cvt_pk_bf16_f32 v130, v163, v164
	v_cvt_pk_bf16_f32 v131, v161, v162
	v_or_b32_e32 v161, s11, v154
	v_mad_i64_i32 v[132:133], s[52:53], v161, s90, v[132:133]
	v_lshl_add_u64 v[132:133], v[132:133], 0, v[148:149]
	global_store_dwordx4 v[132:133], v[128:131], off sc1
	v_add_co_u32_e32 v134, vcc, s91, v134
	s_nop 0
	v_cndmask_b32_e64 v129, v38, v62, s[8:9]
	v_cndmask_b32_e64 v130, v39, v63, s[8:9]
	v_cndmask_b32_e64 v128, v36, v60, s[8:9]
	v_cndmask_b32_e64 v131, v37, v61, s[8:9]
	v_cndmask_b32_e64 v148, v2, v18, s[8:9]
	v_cndmask_b32_e64 v149, v3, v19, s[8:9]
	v_cndmask_b32_e64 v161, v0, v16, s[8:9]
	v_cndmask_b32_e64 v162, v1, v17, s[8:9]
	v_cvt_pk_bf16_f32 v128, v128, v131
	v_cvt_pk_bf16_f32 v129, v129, v130
	v_cvt_pk_bf16_f32 v130, v161, v162
	v_addc_co_u32_e32 v135, vcc, 0, v135, vcc
	v_cvt_pk_bf16_f32 v131, v148, v149
	global_store_dwordx4 v[134:135], v[128:131], off offset:1536 sc1
	v_cndmask_b32_e64 v148, v4, v12, s[8:9]
	v_cndmask_b32_e64 v149, v5, v13, s[8:9]
	v_cndmask_b32_e64 v129, v34, v58, s[8:9]
	v_cndmask_b32_e64 v130, v35, v59, s[8:9]
	v_cndmask_b32_e64 v128, v32, v56, s[8:9]
	v_add_co_u32_e32 v132, vcc, 0x1000, v132
	v_cndmask_b32_e64 v131, v33, v57, s[8:9]
	v_cvt_pk_bf16_f32 v128, v128, v131
	v_cvt_pk_bf16_f32 v129, v129, v130
	v_cvt_pk_bf16_f32 v130, v148, v149
	s_nop 0
	v_addc_co_u32_e32 v133, vcc, 0, v133, vcc
	v_mov_b64_e32 v[148:149], v[150:151]
	v_cndmask_b32_e64 v134, v6, v14, s[8:9]
	v_cndmask_b32_e64 v135, v7, v15, s[8:9]
	v_cvt_pk_bf16_f32 v131, v134, v135
	global_store_dwordx4 v[132:133], v[128:131], off offset:1536 sc1
.LBB0_807:
	s_or_b64 exec, exec, s[12:13]
	v_lshlrev_b64 v[166:167], 2, v[148:149]
	v_lshl_add_u64 v[128:129], s[22:23], 0, v[166:167]
	v_lshl_add_u64 v[132:133], s[26:27], 0, v[166:167]
	v_lshl_add_u64 v[162:163], s[36:37], 0, v[166:167]
	v_lshl_add_u64 v[166:167], s[24:25], 0, v[166:167]
	global_load_dwordx4 v[128:131], v[128:129], off
	v_mov_b32_dpp v172, v116 row_ror:1 row_mask:0xf bank_mask:0xf bound_ctrl:1
	global_load_dwordx4 v[166:169], v[166:167], off
	v_mov_b32_dpp v161, v108 row_shr:1 row_mask:0xf bank_mask:0xf bound_ctrl:1
	global_load_dwordx4 v[132:135], v[132:133], off
	v_mov_b32_dpp v174, v112 row_ror:15 row_mask:0xf bank_mask:0xf bound_ctrl:1
	global_load_dwordx4 v[162:165], v[162:163], off
	v_mov_b32_dpp v181, v84 row_shl:1 row_mask:0xf bank_mask:0xf bound_ctrl:1
	v_mov_b32_dpp v173, v117 row_ror:1 row_mask:0xf bank_mask:0xf bound_ctrl:1
	v_mov_b32_dpp v183, v109 row_shr:1 row_mask:0xf bank_mask:0xf bound_ctrl:1
	v_mov_b32_dpp v175, v113 row_ror:15 row_mask:0xf bank_mask:0xf bound_ctrl:1
	v_mov_b32_dpp v184, v85 row_shl:1 row_mask:0xf bank_mask:0xf bound_ctrl:1
	v_mov_b32_dpp v176, v118 row_ror:1 row_mask:0xf bank_mask:0xf bound_ctrl:1
	v_mov_b32_dpp v185, v110 row_shr:1 row_mask:0xf bank_mask:0xf bound_ctrl:1
	v_mov_b32_dpp v177, v119 row_ror:1 row_mask:0xf bank_mask:0xf bound_ctrl:1
	v_mov_b32_dpp v187, v111 row_shr:1 row_mask:0xf bank_mask:0xf bound_ctrl:1
	v_mov_b32_dpp v179, v115 row_ror:15 row_mask:0xf bank_mask:0xf bound_ctrl:1
	v_mov_b32_dpp v188, v87 row_shl:1 row_mask:0xf bank_mask:0xf bound_ctrl:1
	v_cndmask_b32_e64 v180, v161, v172, s[8:9]
	v_cndmask_b32_e64 v182, v181, v174, s[4:5]
	v_cndmask_b32_e64 v181, v183, v173, s[8:9]
	v_cndmask_b32_e64 v183, v184, v175, s[4:5]
	v_cndmask_b32_e64 v184, v185, v176, s[8:9]
	v_cndmask_b32_e64 v185, v187, v177, s[8:9]
	v_cndmask_b32_e64 v187, v188, v179, s[4:5]
	v_mov_b32_dpp v178, v114 row_ror:15 row_mask:0xf bank_mask:0xf bound_ctrl:1
	v_mov_b32_dpp v186, v86 row_shl:1 row_mask:0xf bank_mask:0xf bound_ctrl:1
	v_cndmask_b32_e64 v186, v186, v178, s[4:5]
	v_mov_b32_dpp v161, v68 row_shr:1 row_mask:0xf bank_mask:0xf bound_ctrl:1
	s_waitcnt vmcnt(0)
;     __device__ __forceinline__ void operator()(f32x4 (&acc)[2][2][4][2], const Unit& u, int wr, int wc, int fr, int fq) const {
;     ...
;                 const int col = bj * DFF + J0 + n * 4;
;                 const float csc = bj ? 0.6931471805599453f : 1.4426950408889634f;
;                 const f32x4 k0 = *(const f32x4*)(cw + col) * csc, k1 = *(const f32x4*)(cw + 2 * DFF + col) * csc, k2 = *(const f32x4*)(cw + 4 * DFF + col) * csc, kb = *(const f32x4*)(cb + col) * csc;
;                 const f32x4 a0 = acc[0][bj][0][n], a1 = acc[0][bj][1][n], a2 = acc[0][bj][2][n], a3 = acc[0][bj][3][n];
;                 const f32x4 b0 = acc[1][bj][0][n], b1 = acc[1][bj][1][n], b2 = acc[1][bj][2][n], b3 = acc[1][bj][3][n];
;                 f32x4 pa, pb, na, nb;
; #pragma unroll
;                 for (int j = 0; j < 4; ++j) {
;                     const float t = dpp_f<0x121>(a3[j]);
;                     const float s1 = dpp_f<0x111>(b3[j]);
;                     const float un = dpp_f<0x12F>(b0[j]);
;                     const float s0 = dpp_f<0x101>(a0[j]);
;                     pa[j] = t; pb[j] = f0 ? t : s1; na[j] = f15 ? un : s0; nb[j] = un; }
;                 f32x4 o0 = k2 * a1 + (k1 * a0 + (k0 * pa + kb)), o1 = k2 * a2 + (k1 * a1 + (k0 * a0 + kb)), o2 = k2 * a3 + (k1 * a2 + (k0 * a1 + kb)), o3 = k2 * na + (k1 * a3 + (k0 * a2 + kb));
;                 f32x4 q0 = k2 * b1 + (k1 * b0 + (k0 * pb + kb)), q1 = k2 * b2 + (k1 * b1 + (k0 * b0 + kb)), q2 = k2 * b3 + (k1 * b2 + (k0 * b1 + kb)), q3 = k2 * nb + (k1 * b3 + (k0 * b2 + kb));
	v_pk_mul_f32 v[128:129], v[128:129], s[40:41] op_sel_hi:[1,0]
	v_pk_mul_f32 v[130:131], v[130:131], s[40:41] op_sel_hi:[1,0]
	v_pk_mul_f32 v[166:167], v[166:167], s[40:41] op_sel_hi:[1,0]
	v_pk_mul_f32 v[168:169], v[168:169], s[40:41] op_sel_hi:[1,0]
	v_pk_mul_f32 v[132:133], v[132:133], s[40:41] op_sel_hi:[1,0]
	v_pk_fma_f32 v[172:173], v[128:129], v[172:173], v[166:167]
	v_pk_mul_f32 v[134:135], v[134:135], s[40:41] op_sel_hi:[1,0]
	v_pk_mul_f32 v[162:163], v[162:163], s[40:41] op_sel_hi:[1,0]
	v_pk_fma_f32 v[176:177], v[130:131], v[176:177], v[168:169]
	v_pk_fma_f32 v[188:189], v[84:85], v[128:129], v[166:167]
	v_pk_fma_f32 v[190:191], v[86:87], v[130:131], v[168:169]
	v_pk_fma_f32 v[192:193], v[124:125], v[128:129], v[166:167]
	v_pk_fma_f32 v[194:195], v[126:127], v[130:131], v[168:169]
	v_pk_fma_f32 v[196:197], v[120:121], v[128:129], v[166:167]
	v_pk_fma_f32 v[198:199], v[122:123], v[130:131], v[168:169]
	v_pk_fma_f32 v[180:181], v[128:129], v[180:181], v[166:167]
	v_pk_fma_f32 v[184:185], v[130:131], v[184:185], v[168:169]
	v_pk_fma_f32 v[200:201], v[112:113], v[128:129], v[166:167]
	v_pk_fma_f32 v[202:203], v[114:115], v[130:131], v[168:169]
	v_pk_fma_f32 v[204:205], v[104:105], v[128:129], v[166:167]
	v_pk_fma_f32 v[206:207], v[106:107], v[130:131], v[168:169]
	v_pk_fma_f32 v[166:167], v[100:101], v[128:129], v[166:167]
	v_pk_fma_f32 v[128:129], v[102:103], v[130:131], v[168:169]
	v_pk_fma_f32 v[84:85], v[84:85], v[132:133], v[172:173]
	v_pk_fma_f32 v[86:87], v[86:87], v[134:135], v[176:177]
	v_pk_fma_f32 v[168:169], v[126:127], v[134:135], v[190:191]
	v_pk_fma_f32 v[172:173], v[124:125], v[132:133], v[188:189]
	v_pk_fma_f32 v[176:177], v[122:123], v[134:135], v[194:195]
	v_pk_fma_f32 v[188:189], v[120:121], v[132:133], v[192:193]
	v_pk_fma_f32 v[190:191], v[118:119], v[134:135], v[198:199]
	v_pk_fma_f32 v[192:193], v[116:117], v[132:133], v[196:197]
	v_pk_fma_f32 v[114:115], v[114:115], v[134:135], v[184:185]
	v_pk_fma_f32 v[112:113], v[112:113], v[132:133], v[180:181]
	v_pk_fma_f32 v[180:181], v[106:107], v[134:135], v[202:203]
	v_pk_fma_f32 v[184:185], v[104:105], v[132:133], v[200:201]
	v_pk_fma_f32 v[194:195], v[102:103], v[134:135], v[206:207]
	v_pk_fma_f32 v[196:197], v[100:101], v[132:133], v[204:205]
	v_pk_fma_f32 v[134:135], v[110:111], v[134:135], v[128:129]
	v_pk_fma_f32 v[128:129], v[124:125], v[162:163], v[84:85]
	v_pk_fma_f32 v[84:85], v[108:109], v[132:133], v[166:167]
	v_or_b32_e32 v132, 4, v150
	v_pk_mul_f32 v[164:165], v[164:165], s[40:41] op_sel_hi:[1,0]
	v_ashrrev_i32_e32 v133, 31, v132
	v_lshlrev_b64 v[166:167], 2, v[148:149]
	v_pk_fma_f32 v[130:131], v[126:127], v[164:165], v[86:87]
	v_pk_fma_f32 v[124:125], v[120:121], v[162:163], v[172:173]
	v_pk_fma_f32 v[126:127], v[122:123], v[164:165], v[168:169]
	v_pk_fma_f32 v[120:121], v[116:117], v[162:163], v[188:189]
	v_pk_fma_f32 v[122:123], v[118:119], v[164:165], v[176:177]
	v_pk_fma_f32 v[116:117], v[162:163], v[182:183], v[192:193]
	v_pk_fma_f32 v[118:119], v[164:165], v[186:187], v[190:191]
	v_pk_fma_f32 v[112:113], v[104:105], v[162:163], v[112:113]
	v_pk_fma_f32 v[114:115], v[106:107], v[164:165], v[114:115]
	v_pk_fma_f32 v[104:105], v[100:101], v[162:163], v[184:185]
	v_pk_fma_f32 v[106:107], v[102:103], v[164:165], v[180:181]
	v_pk_fma_f32 v[100:101], v[108:109], v[162:163], v[196:197]
	v_pk_fma_f32 v[102:103], v[110:111], v[164:165], v[194:195]
	v_pk_fma_f32 v[84:85], v[162:163], v[174:175], v[84:85]
	v_pk_fma_f32 v[86:87], v[164:165], v[178:179], v[134:135]
	v_lshl_add_u64 v[108:109], s[22:23], 0, v[166:167]
	v_lshlrev_b64 v[162:163], 2, v[132:133]
	v_lshl_add_u64 v[166:167], s[24:25], 0, v[166:167]
	global_load_dwordx4 v[108:111], v[108:109], off offset:16
	v_lshl_add_u64 v[132:133], s[26:27], 0, v[162:163]
	global_load_dwordx4 v[166:169], v[166:167], off offset:16
	v_lshl_add_u64 v[162:163], s[36:37], 0, v[162:163]
	global_load_dwordx4 v[132:135], v[132:133], off
	v_mov_b32_dpp v174, v88 row_ror:15 row_mask:0xf bank_mask:0xf bound_ctrl:1
	global_load_dwordx4 v[162:165], v[162:163], off
	v_mov_b32_dpp v181, v76 row_shl:1 row_mask:0xf bank_mask:0xf bound_ctrl:1
	v_mov_b32_dpp v173, v93 row_ror:1 row_mask:0xf bank_mask:0xf bound_ctrl:1
	v_mov_b32_dpp v183, v69 row_shr:1 row_mask:0xf bank_mask:0xf bound_ctrl:1
	v_mov_b32_dpp v175, v89 row_ror:15 row_mask:0xf bank_mask:0xf bound_ctrl:1
	v_mov_b32_dpp v184, v77 row_shl:1 row_mask:0xf bank_mask:0xf bound_ctrl:1
	v_mov_b32_dpp v176, v94 row_ror:1 row_mask:0xf bank_mask:0xf bound_ctrl:1
	v_mov_b32_dpp v185, v70 row_shr:1 row_mask:0xf bank_mask:0xf bound_ctrl:1
	v_mov_b32_dpp v177, v95 row_ror:1 row_mask:0xf bank_mask:0xf bound_ctrl:1
	v_mov_b32_dpp v187, v71 row_shr:1 row_mask:0xf bank_mask:0xf bound_ctrl:1
	v_mov_b32_dpp v179, v91 row_ror:15 row_mask:0xf bank_mask:0xf bound_ctrl:1
	v_mov_b32_dpp v188, v79 row_shl:1 row_mask:0xf bank_mask:0xf bound_ctrl:1
	v_mov_b32_dpp v172, v92 row_ror:1 row_mask:0xf bank_mask:0xf bound_ctrl:1
	v_cndmask_b32_e64 v182, v181, v174, s[4:5]
	v_cndmask_b32_e64 v181, v183, v173, s[8:9]
	v_cndmask_b32_e64 v183, v184, v175, s[4:5]
	v_cndmask_b32_e64 v184, v185, v176, s[8:9]
	v_cndmask_b32_e64 v185, v187, v177, s[8:9]
	v_cndmask_b32_e64 v187, v188, v179, s[4:5]
	v_cndmask_b32_e64 v180, v161, v172, s[8:9]
	v_mov_b32_dpp v186, v78 row_shl:1 row_mask:0xf bank_mask:0xf bound_ctrl:1
	v_mov_b32_dpp v178, v90 row_ror:15 row_mask:0xf bank_mask:0xf bound_ctrl:1
	v_lshlrev_b64 v[150:151], 2, v[150:151]
	v_cndmask_b32_e64 v186, v186, v178, s[4:5]
	v_mov_b32_dpp v161, v32 row_shr:1 row_mask:0xf bank_mask:0xf bound_ctrl:1
	s_waitcnt vmcnt(0)
;     __device__ __forceinline__ void operator()(f32x4 (&acc)[2][2][4][2], const Unit& u, int wr, int wc, int fr, int fq) const {
;     ...
;                 const int col = bj * DFF + J0 + n * 4;
;                 const float csc = bj ? 0.6931471805599453f : 1.4426950408889634f;
;                 const f32x4 k0 = *(const f32x4*)(cw + col) * csc, k1 = *(const f32x4*)(cw + 2 * DFF + col) * csc, k2 = *(const f32x4*)(cw + 4 * DFF + col) * csc, kb = *(const f32x4*)(cb + col) * csc;
;                 const f32x4 a0 = acc[0][bj][0][n], a1 = acc[0][bj][1][n], a2 = acc[0][bj][2][n], a3 = acc[0][bj][3][n];
;                 const f32x4 b0 = acc[1][bj][0][n], b1 = acc[1][bj][1][n], b2 = acc[1][bj][2][n], b3 = acc[1][bj][3][n];
;                 f32x4 pa, pb, na, nb;
; #pragma unroll
;                 for (int j = 0; j < 4; ++j) {
;                     const float t = dpp_f<0x121>(a3[j]);
;                     const float s1 = dpp_f<0x111>(b3[j]);
;                     const float un = dpp_f<0x12F>(b0[j]);
;                     const float s0 = dpp_f<0x101>(a0[j]);
;                     pa[j] = t; pb[j] = f0 ? t : s1; na[j] = f15 ? un : s0; nb[j] = un; }
;                 f32x4 o0 = k2 * a1 + (k1 * a0 + (k0 * pa + kb)), o1 = k2 * a2 + (k1 * a1 + (k0 * a0 + kb)), o2 = k2 * a3 + (k1 * a2 + (k0 * a1 + kb)), o3 = k2 * na + (k1 * a3 + (k0 * a2 + kb));
;                 f32x4 q0 = k2 * b1 + (k1 * b0 + (k0 * pb + kb)), q1 = k2 * b2 + (k1 * b1 + (k0 * b0 + kb)), q2 = k2 * b3 + (k1 * b2 + (k0 * b1 + kb)), q3 = k2 * nb + (k1 * b3 + (k0 * b2 + kb));
	v_pk_mul_f32 v[188:189], v[110:111], s[40:41] op_sel_hi:[1,0]
	v_pk_mul_f32 v[190:191], v[108:109], s[40:41] op_sel_hi:[1,0]
	v_pk_mul_f32 v[168:169], v[168:169], s[40:41] op_sel_hi:[1,0]
	v_pk_mul_f32 v[166:167], v[166:167], s[40:41] op_sel_hi:[1,0]
	v_pk_mul_f32 v[192:193], v[134:135], s[40:41] op_sel_hi:[1,0]
	v_pk_mul_f32 v[194:195], v[132:133], s[40:41] op_sel_hi:[1,0]
	v_pk_fma_f32 v[108:109], v[190:191], v[172:173], v[166:167]
	v_pk_fma_f32 v[110:111], v[188:189], v[176:177], v[168:169]
	v_pk_mul_f32 v[164:165], v[164:165], s[40:41] op_sel_hi:[1,0]
	v_pk_mul_f32 v[162:163], v[162:163], s[40:41] op_sel_hi:[1,0]
	v_pk_fma_f32 v[132:133], v[76:77], v[190:191], v[166:167]
	v_pk_fma_f32 v[134:135], v[78:79], v[188:189], v[168:169]
	v_pk_fma_f32 v[180:181], v[190:191], v[180:181], v[166:167]
	v_pk_fma_f32 v[184:185], v[188:189], v[184:185], v[168:169]
	v_pk_fma_f32 v[200:201], v[88:89], v[190:191], v[166:167]
	v_pk_fma_f32 v[202:203], v[90:91], v[188:189], v[168:169]
	v_pk_fma_f32 v[78:79], v[78:79], v[192:193], v[110:111]
	v_pk_fma_f32 v[76:77], v[76:77], v[194:195], v[108:109]
	v_pk_fma_f32 v[172:173], v[72:73], v[190:191], v[166:167]
	v_pk_fma_f32 v[176:177], v[74:75], v[188:189], v[168:169]
	v_pk_fma_f32 v[108:109], v[74:75], v[192:193], v[134:135]
	v_pk_fma_f32 v[204:205], v[72:73], v[194:195], v[132:133]
	v_pk_fma_f32 v[90:91], v[90:91], v[192:193], v[184:185]
	v_pk_fma_f32 v[88:89], v[88:89], v[194:195], v[180:181]
	v_pk_fma_f32 v[180:181], v[82:83], v[192:193], v[202:203]
	v_pk_fma_f32 v[184:185], v[80:81], v[194:195], v[200:201]
	v_pk_fma_f32 v[132:133], v[72:73], v[162:163], v[76:77]
	v_pk_fma_f32 v[134:135], v[74:75], v[164:165], v[78:79]
	v_pk_fma_f32 v[72:73], v[80:81], v[190:191], v[166:167]
	v_pk_fma_f32 v[74:75], v[82:83], v[188:189], v[168:169]
	v_pk_fma_f32 v[196:197], v[96:97], v[190:191], v[166:167]
	v_pk_fma_f32 v[198:199], v[98:99], v[188:189], v[168:169]
	v_pk_fma_f32 v[78:79], v[66:67], v[164:165], v[180:181]
	v_pk_fma_f32 v[76:77], v[64:65], v[162:163], v[184:185]
	v_pk_fma_f32 v[74:75], v[66:67], v[192:193], v[74:75]
	v_pk_fma_f32 v[72:73], v[64:65], v[194:195], v[72:73]
	v_pk_fma_f32 v[64:65], v[64:65], v[190:191], v[166:167]
	v_pk_fma_f32 v[66:67], v[66:67], v[188:189], v[168:169]
	v_pk_fma_f32 v[176:177], v[98:99], v[192:193], v[176:177]
	v_pk_fma_f32 v[172:173], v[96:97], v[194:195], v[172:173]
	v_pk_fma_f32 v[198:199], v[94:95], v[192:193], v[198:199]
	v_pk_fma_f32 v[196:197], v[92:93], v[194:195], v[196:197]
	v_pk_fma_f32 v[66:67], v[70:71], v[192:193], v[66:67]
	v_pk_fma_f32 v[64:65], v[68:69], v[194:195], v[64:65]
	v_lshl_add_u64 v[166:167], v[150:151], 0, s[42:43]
	v_pk_fma_f32 v[110:111], v[98:99], v[164:165], v[108:109]
	v_pk_fma_f32 v[108:109], v[96:97], v[162:163], v[204:205]
	v_pk_fma_f32 v[98:99], v[94:95], v[164:165], v[176:177]
	v_pk_fma_f32 v[96:97], v[92:93], v[162:163], v[172:173]
	v_pk_fma_f32 v[92:93], v[162:163], v[182:183], v[196:197]
	v_pk_fma_f32 v[94:95], v[164:165], v[186:187], v[198:199]
	v_pk_fma_f32 v[90:91], v[82:83], v[164:165], v[90:91]
	v_pk_fma_f32 v[88:89], v[80:81], v[162:163], v[88:89]
	v_pk_fma_f32 v[74:75], v[70:71], v[164:165], v[74:75]
	v_pk_fma_f32 v[72:73], v[68:69], v[162:163], v[72:73]
	v_pk_fma_f32 v[66:67], v[164:165], v[178:179], v[66:67]
	v_pk_fma_f32 v[64:65], v[162:163], v[174:175], v[64:65]
	v_lshl_add_u64 v[68:69], s[22:23], 0, v[166:167]
	v_lshl_add_u64 v[80:81], s[26:27], 0, v[166:167]
	v_lshl_add_u64 v[162:163], s[36:37], 0, v[166:167]
	v_lshl_add_u64 v[166:167], s[24:25], 0, v[166:167]
	global_load_dwordx4 v[68:71], v[68:69], off
	v_mov_b32_dpp v172, v48 row_ror:1 row_mask:0xf bank_mask:0xf bound_ctrl:1
	global_load_dwordx4 v[166:169], v[166:167], off
	v_mov_b32_dpp v174, v44 row_ror:15 row_mask:0xf bank_mask:0xf bound_ctrl:1
	global_load_dwordx4 v[80:83], v[80:81], off
	v_mov_b32_dpp v181, v60 row_shl:1 row_mask:0xf bank_mask:0xf bound_ctrl:1
	global_load_dwordx4 v[162:165], v[162:163], off
	v_mov_b32_dpp v173, v49 row_ror:1 row_mask:0xf bank_mask:0xf bound_ctrl:1
	v_mov_b32_dpp v183, v33 row_shr:1 row_mask:0xf bank_mask:0xf bound_ctrl:1
	v_mov_b32_dpp v175, v45 row_ror:15 row_mask:0xf bank_mask:0xf bound_ctrl:1
	v_mov_b32_dpp v184, v61 row_shl:1 row_mask:0xf bank_mask:0xf bound_ctrl:1
	v_mov_b32_dpp v176, v50 row_ror:1 row_mask:0xf bank_mask:0xf bound_ctrl:1
	v_mov_b32_dpp v185, v34 row_shr:1 row_mask:0xf bank_mask:0xf bound_ctrl:1
	v_mov_b32_dpp v177, v51 row_ror:1 row_mask:0xf bank_mask:0xf bound_ctrl:1
	v_mov_b32_dpp v187, v35 row_shr:1 row_mask:0xf bank_mask:0xf bound_ctrl:1
	v_mov_b32_dpp v179, v47 row_ror:15 row_mask:0xf bank_mask:0xf bound_ctrl:1
	v_mov_b32_dpp v188, v63 row_shl:1 row_mask:0xf bank_mask:0xf bound_ctrl:1
	v_cndmask_b32_e64 v180, v161, v172, s[8:9]
	v_cndmask_b32_e64 v182, v181, v174, s[4:5]
	v_cndmask_b32_e64 v181, v183, v173, s[8:9]
	v_cndmask_b32_e64 v183, v184, v175, s[4:5]
	v_cndmask_b32_e64 v184, v185, v176, s[8:9]
	v_cndmask_b32_e64 v185, v187, v177, s[8:9]
	v_cndmask_b32_e64 v187, v188, v179, s[4:5]
	v_mov_b32_dpp v178, v46 row_ror:15 row_mask:0xf bank_mask:0xf bound_ctrl:1
	v_mov_b32_dpp v186, v62 row_shl:1 row_mask:0xf bank_mask:0xf bound_ctrl:1
	v_cndmask_b32_e64 v186, v186, v178, s[4:5]
	v_lshl_add_u64 v[150:151], v[150:151], 0, s[46:47]
	v_mov_b32_dpp v161, v4 row_shr:1 row_mask:0xf bank_mask:0xf bound_ctrl:1
	s_waitcnt vmcnt(0)
;     __device__ __forceinline__ void operator()(f32x4 (&acc)[2][2][4][2], const Unit& u, int wr, int wc, int fr, int fq) const {
;     ...
;                 const int col = bj * DFF + J0 + n * 4;
;                 const float csc = bj ? 0.6931471805599453f : 1.4426950408889634f;
;                 const f32x4 k0 = *(const f32x4*)(cw + col) * csc, k1 = *(const f32x4*)(cw + 2 * DFF + col) * csc, k2 = *(const f32x4*)(cw + 4 * DFF + col) * csc, kb = *(const f32x4*)(cb + col) * csc;
;                 const f32x4 a0 = acc[0][bj][0][n], a1 = acc[0][bj][1][n], a2 = acc[0][bj][2][n], a3 = acc[0][bj][3][n];
;                 const f32x4 b0 = acc[1][bj][0][n], b1 = acc[1][bj][1][n], b2 = acc[1][bj][2][n], b3 = acc[1][bj][3][n];
;                 f32x4 pa, pb, na, nb;
; #pragma unroll
;                 for (int j = 0; j < 4; ++j) {
;                     const float t = dpp_f<0x121>(a3[j]);
;                     const float s1 = dpp_f<0x111>(b3[j]);
;                     const float un = dpp_f<0x12F>(b0[j]);
;                     const float s0 = dpp_f<0x101>(a0[j]);
;                     pa[j] = t; pb[j] = f0 ? t : s1; na[j] = f15 ? un : s0; nb[j] = un; }
;                 f32x4 o0 = k2 * a1 + (k1 * a0 + (k0 * pa + kb)), o1 = k2 * a2 + (k1 * a1 + (k0 * a0 + kb)), o2 = k2 * a3 + (k1 * a2 + (k0 * a1 + kb)), o3 = k2 * na + (k1 * a3 + (k0 * a2 + kb));
;                 f32x4 q0 = k2 * b1 + (k1 * b0 + (k0 * pb + kb)), q1 = k2 * b2 + (k1 * b1 + (k0 * b0 + kb)), q2 = k2 * b3 + (k1 * b2 + (k0 * b1 + kb)), q3 = k2 * nb + (k1 * b3 + (k0 * b2 + kb));
	v_pk_mul_f32 v[188:189], v[70:71], s[44:45] op_sel_hi:[1,0]
	v_pk_mul_f32 v[190:191], v[68:69], s[44:45] op_sel_hi:[1,0]
	v_pk_mul_f32 v[168:169], v[168:169], s[44:45] op_sel_hi:[1,0]
	v_pk_mul_f32 v[166:167], v[166:167], s[44:45] op_sel_hi:[1,0]
	v_pk_mul_f32 v[80:81], v[80:81], s[44:45] op_sel_hi:[1,0]
	v_pk_mul_f32 v[82:83], v[82:83], s[44:45] op_sel_hi:[1,0]
	v_pk_fma_f32 v[68:69], v[190:191], v[172:173], v[166:167]
	v_pk_fma_f32 v[70:71], v[188:189], v[176:177], v[168:169]
	v_pk_fma_f32 v[192:193], v[56:57], v[190:191], v[166:167]
	v_pk_fma_f32 v[194:195], v[58:59], v[188:189], v[168:169]
	v_pk_fma_f32 v[180:181], v[190:191], v[180:181], v[166:167]
	v_pk_fma_f32 v[184:185], v[188:189], v[184:185], v[168:169]
	v_pk_mul_f32 v[164:165], v[164:165], s[44:45] op_sel_hi:[1,0]
	v_pk_mul_f32 v[162:163], v[162:163], s[44:45] op_sel_hi:[1,0]
	v_pk_fma_f32 v[172:173], v[60:61], v[190:191], v[166:167]
	v_pk_fma_f32 v[176:177], v[62:63], v[188:189], v[168:169]
	v_pk_fma_f32 v[196:197], v[52:53], v[190:191], v[166:167]
	v_pk_fma_f32 v[198:199], v[54:55], v[188:189], v[168:169]
	v_pk_fma_f32 v[62:63], v[62:63], v[82:83], v[70:71]
	v_pk_fma_f32 v[60:61], v[60:61], v[80:81], v[68:69]
	v_pk_fma_f32 v[194:195], v[54:55], v[82:83], v[194:195]
	v_pk_fma_f32 v[192:193], v[52:53], v[80:81], v[192:193]
	v_pk_fma_f32 v[184:185], v[46:47], v[82:83], v[184:185]
	v_pk_fma_f32 v[180:181], v[44:45], v[80:81], v[180:181]
	v_pk_fma_f32 v[44:45], v[44:45], v[190:191], v[166:167]
	v_pk_fma_f32 v[46:47], v[46:47], v[188:189], v[168:169]
	v_pk_fma_f32 v[176:177], v[58:59], v[82:83], v[176:177]
	v_pk_fma_f32 v[172:173], v[56:57], v[80:81], v[172:173]
	v_pk_fma_f32 v[198:199], v[50:51], v[82:83], v[198:199]
	v_pk_fma_f32 v[196:197], v[48:49], v[80:81], v[196:197]
	v_pk_fma_f32 v[68:69], v[56:57], v[162:163], v[60:61]
	v_pk_fma_f32 v[70:71], v[58:59], v[164:165], v[62:63]
	v_pk_fma_f32 v[56:57], v[48:49], v[162:163], v[192:193]
	v_pk_fma_f32 v[58:59], v[50:51], v[164:165], v[194:195]
	v_pk_fma_f32 v[48:49], v[40:41], v[162:163], v[180:181]
	v_pk_fma_f32 v[50:51], v[42:43], v[164:165], v[184:185]
	v_pk_fma_f32 v[46:47], v[42:43], v[82:83], v[46:47]
	v_pk_fma_f32 v[44:45], v[40:41], v[80:81], v[44:45]
	v_pk_fma_f32 v[40:41], v[40:41], v[190:191], v[166:167]
	v_pk_fma_f32 v[42:43], v[42:43], v[188:189], v[168:169]
	v_pk_fma_f32 v[44:45], v[36:37], v[162:163], v[44:45]
	v_pk_fma_f32 v[46:47], v[38:39], v[164:165], v[46:47]
	v_pk_fma_f32 v[42:43], v[38:39], v[82:83], v[42:43]
	v_pk_fma_f32 v[40:41], v[36:37], v[80:81], v[40:41]
	v_pk_fma_f32 v[36:37], v[36:37], v[190:191], v[166:167]
	v_pk_fma_f32 v[38:39], v[38:39], v[188:189], v[168:169]
	v_pk_fma_f32 v[40:41], v[32:33], v[162:163], v[40:41]
	v_pk_fma_f32 v[42:43], v[34:35], v[164:165], v[42:43]
	v_pk_fma_f32 v[34:35], v[34:35], v[82:83], v[38:39]
	v_pk_fma_f32 v[32:33], v[32:33], v[80:81], v[36:37]
	v_pk_fma_f32 v[60:61], v[52:53], v[162:163], v[172:173]
	v_pk_fma_f32 v[62:63], v[54:55], v[164:165], v[176:177]
	v_pk_fma_f32 v[52:53], v[162:163], v[182:183], v[196:197]
	v_pk_fma_f32 v[54:55], v[164:165], v[186:187], v[198:199]
	v_pk_fma_f32 v[32:33], v[162:163], v[174:175], v[32:33]
	v_pk_fma_f32 v[34:35], v[164:165], v[178:179], v[34:35]
	v_lshl_add_u64 v[36:37], s[22:23], 0, v[150:151]
	v_lshl_add_u64 v[80:81], s[26:27], 0, v[150:151]
	v_lshl_add_u64 v[162:163], s[36:37], 0, v[150:151]
	v_lshl_add_u64 v[150:151], s[24:25], 0, v[150:151]
	global_load_dwordx4 v[36:39], v[36:37], off
	v_mov_b32_dpp v172, v20 row_ror:15 row_mask:0xf bank_mask:0xf bound_ctrl:1
	global_load_dwordx4 v[166:169], v[150:151], off
	v_mov_b32_dpp v150, v24 row_ror:1 row_mask:0xf bank_mask:0xf bound_ctrl:1
	global_load_dwordx4 v[80:83], v[80:81], off
	v_mov_b32_dpp v151, v25 row_ror:1 row_mask:0xf bank_mask:0xf bound_ctrl:1
	global_load_dwordx4 v[162:165], v[162:163], off
	v_mov_b32_dpp v179, v16 row_shl:1 row_mask:0xf bank_mask:0xf bound_ctrl:1
	v_mov_b32_dpp v181, v5 row_shr:1 row_mask:0xf bank_mask:0xf bound_ctrl:1
	v_mov_b32_dpp v182, v17 row_shl:1 row_mask:0xf bank_mask:0xf bound_ctrl:1
	v_cndmask_b32_e64 v178, v161, v150, s[8:9]
	v_cndmask_b32_e64 v180, v179, v172, s[4:5]
	v_cndmask_b32_e64 v179, v181, v151, s[8:9]
	v_mov_b32_dpp v173, v21 row_ror:15 row_mask:0xf bank_mask:0xf bound_ctrl:1
	v_mov_b32_dpp v174, v26 row_ror:1 row_mask:0xf bank_mask:0xf bound_ctrl:1
	v_mov_b32_dpp v183, v6 row_shr:1 row_mask:0xf bank_mask:0xf bound_ctrl:1
	v_mov_b32_dpp v175, v27 row_ror:1 row_mask:0xf bank_mask:0xf bound_ctrl:1
	v_mov_b32_dpp v185, v7 row_shr:1 row_mask:0xf bank_mask:0xf bound_ctrl:1
	v_mov_b32_dpp v177, v23 row_ror:15 row_mask:0xf bank_mask:0xf bound_ctrl:1
	v_mov_b32_dpp v186, v19 row_shl:1 row_mask:0xf bank_mask:0xf bound_ctrl:1
	v_cndmask_b32_e64 v181, v182, v173, s[4:5]
	v_cndmask_b32_e64 v182, v183, v174, s[8:9]
	v_cndmask_b32_e64 v183, v185, v175, s[8:9]
	v_cndmask_b32_e64 v185, v186, v177, s[4:5]
	v_mov_b32_dpp v184, v18 row_shl:1 row_mask:0xf bank_mask:0xf bound_ctrl:1
	v_mov_b32_dpp v176, v22 row_ror:15 row_mask:0xf bank_mask:0xf bound_ctrl:1
	v_cndmask_b32_e64 v184, v184, v176, s[4:5]
	s_waitcnt vmcnt(0)
; __device__ __forceinline__ unsigned cvt_pk_bf16(float lo, float hi) { unsigned r; asm volatile("v_cvt_pk_bf16_f32 %0, %1, %2" : "=v"(r) : "v"(lo), "v"(hi)); return r; }
; #define SG2(gx, vx) (((gx) * (vx)) * __builtin_amdgcn_rcpf(1.0f + __builtin_amdgcn_exp2f(-(gx))))
;     __device__ __forceinline__ void operator()(f32x4 (&acc)[2][2][4][2], const Unit& u, int wr, int wc, int fr, int fq) const {
;     ...
;                 f32x4 o0 = k2 * a1 + (k1 * a0 + (k0 * pa + kb)), o1 = k2 * a2 + (k1 * a1 + (k0 * a0 + kb)), o2 = k2 * a3 + (k1 * a2 + (k0 * a1 + kb)), o3 = k2 * na + (k1 * a3 + (k0 * a2 + kb));
;                 f32x4 q0 = k2 * b1 + (k1 * b0 + (k0 * pb + kb)), q1 = k2 * b2 + (k1 * b1 + (k0 * b0 + kb)), q2 = k2 * b3 + (k1 * b2 + (k0 * b1 + kb)), q3 = k2 * nb + (k1 * b3 + (k0 * b2 + kb));
;                 asm volatile("" : "+v"(o0), "+v"(o1), "+v"(o2), "+v"(o3), "+v"(q0), "+v"(q1), "+v"(q2), "+v"(q3));
;                 acc[0][bj][0][n] = o0; acc[0][bj][1][n] = o1; acc[0][bj][2][n] = o2; acc[0][bj][3][n] = o3;
;                 acc[1][bj][0][n] = q0; acc[1][bj][1][n] = q1; acc[1][bj][2][n] = q2; acc[1][bj][3][n] = q3;
;             }
; #pragma unroll
;         for (int ai = 0; ai < 2; ++ai)
; #pragma unroll
;             for (int m = 0; m < 4; ++m) {
;                 const f32x4 g0 = acc[ai][0][m][0], g1 = acc[ai][0][m][1], v0 = acc[ai][1][m][0], v1 = acc[ai][1][m][1];
;     ...
;                 u32x4 w; w.x = cvt_pk_bf16(SG2(g0[0], v0[0]), SG2(g0[1], v0[1])); w.y = cvt_pk_bf16(SG2(g0[2], v0[2]), SG2(g0[3], v0[3]));
;                 w.z = cvt_pk_bf16(SG2(g1[0], v1[0]), SG2(g1[1], v1[1])); w.w = cvt_pk_bf16(SG2(g1[2], v1[2]), SG2(g1[3], v1[3]));
;     ...
;                 const bool valid = !((ai == 0 && m == 0 && f0) || (ai == 1 && m == 3 && f15));
;                 if (valid) *(u32x4*)(A + (size_t)(sc * 128 + ai * 64 + 4 * fr + m) * DFF + J0) = w;
	v_pk_mul_f32 v[188:189], v[36:37], s[44:45] op_sel_hi:[1,0]
	v_pk_mul_f32 v[186:187], v[38:39], s[44:45] op_sel_hi:[1,0]
	v_pk_mul_f32 v[166:167], v[166:167], s[44:45] op_sel_hi:[1,0]
	v_pk_mul_f32 v[168:169], v[168:169], s[44:45] op_sel_hi:[1,0]
	v_pk_mul_f32 v[190:191], v[80:81], s[44:45] op_sel_hi:[1,0]
	v_pk_fma_f32 v[36:37], v[188:189], v[150:151], v[166:167]
	v_pk_mul_f32 v[162:163], v[162:163], s[44:45] op_sel_hi:[1,0]
	v_pk_fma_f32 v[80:81], v[16:17], v[188:189], v[166:167]
	v_pk_fma_f32 v[16:17], v[16:17], v[190:191], v[36:37]
	v_pk_fma_f32 v[150:151], v[12:13], v[188:189], v[166:167]
	v_pk_fma_f32 v[36:37], v[12:13], v[190:191], v[80:81]
	v_pk_fma_f32 v[80:81], v[12:13], v[162:163], v[16:17]
	v_pk_fma_f32 v[12:13], v[188:189], v[178:179], v[166:167]
	v_pk_mul_f32 v[192:193], v[82:83], s[44:45] op_sel_hi:[1,0]
	v_pk_fma_f32 v[12:13], v[20:21], v[190:191], v[12:13]
	v_pk_fma_f32 v[38:39], v[186:187], v[174:175], v[168:169]
	v_pk_fma_f32 v[16:17], v[8:9], v[162:163], v[12:13]
	v_pk_fma_f32 v[12:13], v[20:21], v[188:189], v[166:167]
	v_pk_mul_f32 v[164:165], v[164:165], s[44:45] op_sel_hi:[1,0]
	v_pk_fma_f32 v[12:13], v[8:9], v[190:191], v[12:13]
	v_pk_fma_f32 v[8:9], v[8:9], v[188:189], v[166:167]
	v_pk_fma_f32 v[12:13], v[0:1], v[162:163], v[12:13]
	v_pk_fma_f32 v[8:9], v[0:1], v[190:191], v[8:9]
	v_pk_fma_f32 v[0:1], v[0:1], v[188:189], v[166:167]
	v_pk_fma_f32 v[8:9], v[4:5], v[162:163], v[8:9]
	v_pk_fma_f32 v[0:1], v[4:5], v[190:191], v[0:1]
	v_exp_f32_e64 v4, -v128
	v_exp_f32_e64 v5, -v129
	v_pk_fma_f32 v[82:83], v[18:19], v[186:187], v[168:169]
	v_pk_fma_f32 v[18:19], v[18:19], v[192:193], v[38:39]
	v_pk_fma_f32 v[174:175], v[14:15], v[186:187], v[168:169]
	v_pk_fma_f32 v[38:39], v[14:15], v[192:193], v[82:83]
	v_pk_fma_f32 v[82:83], v[14:15], v[164:165], v[18:19]
	v_pk_fma_f32 v[14:15], v[186:187], v[182:183], v[168:169]
	v_add_f32_e32 v4, 1.0, v4
	v_pk_fma_f32 v[14:15], v[22:23], v[192:193], v[14:15]
	v_rcp_f32_e32 v4, v4
	v_pk_fma_f32 v[18:19], v[10:11], v[164:165], v[14:15]
	v_pk_fma_f32 v[14:15], v[22:23], v[186:187], v[168:169]
	v_add_f32_e32 v5, 1.0, v5
	v_pk_fma_f32 v[14:15], v[10:11], v[192:193], v[14:15]
	v_pk_fma_f32 v[10:11], v[10:11], v[186:187], v[168:169]
	v_rcp_f32_e32 v5, v5
	v_pk_fma_f32 v[14:15], v[2:3], v[164:165], v[14:15]
	v_pk_fma_f32 v[10:11], v[2:3], v[192:193], v[10:11]
	v_pk_fma_f32 v[2:3], v[2:3], v[186:187], v[168:169]
	v_pk_fma_f32 v[194:195], v[28:29], v[188:189], v[166:167]
	v_pk_fma_f32 v[196:197], v[30:31], v[186:187], v[168:169]
	v_pk_fma_f32 v[10:11], v[6:7], v[164:165], v[10:11]
	v_pk_fma_f32 v[2:3], v[6:7], v[192:193], v[2:3]
	v_mul_f32_e32 v6, v128, v68
	v_pk_fma_f32 v[174:175], v[30:31], v[192:193], v[174:175]
	v_pk_fma_f32 v[150:151], v[28:29], v[190:191], v[150:151]
	v_pk_fma_f32 v[196:197], v[26:27], v[192:193], v[196:197]
	v_pk_fma_f32 v[194:195], v[24:25], v[190:191], v[194:195]
	v_mul_f32_e32 v4, v4, v6
	v_mul_f32_e32 v6, v129, v69
	v_pk_fma_f32 v[36:37], v[28:29], v[162:163], v[36:37]
	v_pk_fma_f32 v[38:39], v[30:31], v[164:165], v[38:39]
	v_pk_fma_f32 v[28:29], v[24:25], v[162:163], v[150:151]
	v_pk_fma_f32 v[30:31], v[26:27], v[164:165], v[174:175]
	v_pk_fma_f32 v[24:25], v[162:163], v[180:181], v[194:195]
	v_pk_fma_f32 v[26:27], v[164:165], v[184:185], v[196:197]
	v_pk_fma_f32 v[0:1], v[162:163], v[172:173], v[0:1]
	v_pk_fma_f32 v[2:3], v[164:165], v[176:177], v[2:3]
	v_exp_f32_e64 v7, -v130
	v_mul_f32_e32 v5, v5, v6
	v_cvt_pk_bf16_f32 v4, v4, v5
	v_exp_f32_e64 v5, -v131
	v_add_f32_e32 v6, 1.0, v7
	v_rcp_f32_e32 v6, v6
	v_mul_f32_e32 v7, v130, v70
	v_add_f32_e32 v5, 1.0, v5
	v_rcp_f32_e32 v5, v5
	v_mul_f32_e32 v6, v6, v7
	v_mul_f32_e32 v7, v131, v71
	v_exp_f32_e64 v21, -v132
	v_mul_f32_e32 v5, v5, v7
	v_cvt_pk_bf16_f32 v5, v6, v5
	v_exp_f32_e64 v6, -v133
	v_add_f32_e32 v7, 1.0, v21
	v_rcp_f32_e32 v7, v7
	v_mul_f32_e32 v21, v132, v80
	v_add_f32_e32 v6, 1.0, v6
	v_rcp_f32_e32 v6, v6
	v_mul_f32_e32 v7, v7, v21
	v_mul_f32_e32 v21, v133, v81
	v_exp_f32_e64 v22, -v134
	v_mul_f32_e32 v6, v6, v21
	v_exp_f32_e64 v21, -v135
	v_cvt_pk_bf16_f32 v6, v7, v6
	v_add_f32_e32 v7, 1.0, v22
	v_rcp_f32_e32 v7, v7
	v_add_f32_e32 v21, 1.0, v21
	v_rcp_f32_e32 v21, v21
	v_mul_f32_e32 v22, v134, v82
	v_lshl_or_b32 v20, s10, 7, v155
	v_mul_f32_e32 v7, v7, v22
	v_mul_f32_e32 v22, v135, v83
	v_mul_f32_e32 v21, v21, v22
	v_cvt_pk_bf16_f32 v7, v7, v21
	s_and_saveexec_b64 s[12:13], s[0:1]
	s_cbranch_execz .LBB0_809
	v_mov_b64_e32 v[22:23], s[18:19]
	v_mad_i64_i32 v[22:23], s[10:11], v20, s92, v[22:23]
	v_lshl_add_u64 v[22:23], v[148:149], 1, v[22:23]
	global_store_dwordx4 v[22:23], v[4:7], off sc1
; __device__ __forceinline__ unsigned cvt_pk_bf16(float lo, float hi) { unsigned r; asm volatile("v_cvt_pk_bf16_f32 %0, %1, %2" : "=v"(r) : "v"(lo), "v"(hi)); return r; }
; #define SG2(gx, vx) (((gx) * (vx)) * __builtin_amdgcn_rcpf(1.0f + __builtin_amdgcn_exp2f(-(gx))))
;     __device__ __forceinline__ void operator()(f32x4 (&acc)[2][2][4][2], const Unit& u, int wr, int wc, int fr, int fq) const {
;     ...
;             for (int m = 0; m < 4; ++m) {
;                 const f32x4 g0 = acc[ai][0][m][0], g1 = acc[ai][0][m][1], v0 = acc[ai][1][m][0], v1 = acc[ai][1][m][1];
;     ...
;                 u32x4 w; w.x = cvt_pk_bf16(SG2(g0[0], v0[0]), SG2(g0[1], v0[1])); w.y = cvt_pk_bf16(SG2(g0[2], v0[2]), SG2(g0[3], v0[3]));
;                 w.z = cvt_pk_bf16(SG2(g1[0], v1[0]), SG2(g1[1], v1[1])); w.w = cvt_pk_bf16(SG2(g1[2], v1[2]), SG2(g1[3], v1[3]));
;     ...
;                 const bool valid = !((ai == 0 && m == 0 && f0) || (ai == 1 && m == 3 && f15));
;                 if (valid) *(u32x4*)(A + (size_t)(sc * 128 + ai * 64 + 4 * fr + m) * DFF + J0) = w;
.LBB0_809:
	s_or_b64 exec, exec, s[12:13]
	s_nop 0
	v_exp_f32_e64 v4, -v124
	v_exp_f32_e64 v5, -v125
	v_mul_f32_e32 v6, v124, v60
	v_mul_f32_e32 v7, v125, v61
	v_add_f32_e32 v4, 1.0, v4
	v_add_f32_e32 v5, 1.0, v5
	v_rcp_f32_e32 v4, v4
	v_rcp_f32_e32 v5, v5
	v_exp_f32_e64 v21, -v126
	v_mul_f32_e32 v24, v92, v24
	v_mul_f32_e32 v4, v4, v6
	v_mul_f32_e32 v5, v5, v7
	v_cvt_pk_bf16_f32 v60, v4, v5
	v_exp_f32_e64 v4, -v127
	v_add_f32_e32 v5, 1.0, v21
	v_rcp_f32_e32 v5, v5
	v_mul_f32_e32 v6, v126, v62
	v_add_f32_e32 v4, 1.0, v4
	v_rcp_f32_e32 v4, v4
	v_mul_f32_e32 v5, v5, v6
	v_mul_f32_e32 v6, v127, v63
	v_exp_f32_e64 v7, -v108
	v_mul_f32_e32 v4, v4, v6
	v_cvt_pk_bf16_f32 v61, v5, v4
	v_exp_f32_e64 v4, -v109
	v_add_f32_e32 v5, 1.0, v7
	v_rcp_f32_e32 v5, v5
	v_mul_f32_e32 v6, v108, v36
	v_add_f32_e32 v4, 1.0, v4
	v_rcp_f32_e32 v4, v4
	v_mul_f32_e32 v5, v5, v6
	v_mul_f32_e32 v6, v109, v37
	v_exp_f32_e64 v7, -v110
	v_mul_f32_e32 v4, v4, v6
	v_exp_f32_e64 v6, -v111
	v_cvt_pk_bf16_f32 v62, v5, v4
	v_add_f32_e32 v4, 1.0, v7
	v_rcp_f32_e32 v4, v4
	v_add_f32_e32 v5, 1.0, v6
	v_rcp_f32_e32 v5, v5
	v_mul_f32_e32 v6, v110, v38
	v_mul_f32_e32 v4, v4, v6
	v_mul_f32_e32 v6, v111, v39
	v_mul_f32_e32 v5, v5, v6
	v_cvt_pk_bf16_f32 v63, v4, v5
	v_or_b32_e32 v4, 1, v20
	v_mov_b64_e32 v[6:7], s[18:19]
	v_mad_i64_i32 v[22:23], s[10:11], v4, s92, v[6:7]
	v_lshlrev_b64 v[4:5], 1, v[148:149]
	v_exp_f32_e64 v21, -v120
	v_lshl_add_u64 v[22:23], v[22:23], 0, v[4:5]
	global_store_dwordx4 v[22:23], v[60:63], off sc1
	v_exp_f32_e64 v22, -v121
	v_add_f32_e32 v21, 1.0, v21
	v_rcp_f32_e32 v21, v21
	v_mul_f32_e32 v23, v120, v56
	v_add_f32_e32 v22, 1.0, v22
	v_rcp_f32_e32 v22, v22
	v_mul_f32_e32 v21, v21, v23
	v_mul_f32_e32 v23, v121, v57
	v_exp_f32_e64 v37, -v122
	v_mul_f32_e32 v22, v22, v23
	v_cvt_pk_bf16_f32 v36, v21, v22
	v_exp_f32_e64 v21, -v123
	v_add_f32_e32 v22, 1.0, v37
	v_rcp_f32_e32 v22, v22
	v_mul_f32_e32 v23, v122, v58
	v_add_f32_e32 v21, 1.0, v21
	v_rcp_f32_e32 v21, v21
	v_mul_f32_e32 v22, v22, v23
	v_mul_f32_e32 v23, v123, v59
	v_exp_f32_e64 v38, -v96
	v_mul_f32_e32 v21, v21, v23
	v_cvt_pk_bf16_f32 v37, v22, v21
	v_exp_f32_e64 v21, -v97
	v_add_f32_e32 v22, 1.0, v38
	v_rcp_f32_e32 v22, v22
	v_mul_f32_e32 v23, v96, v28
	v_add_f32_e32 v21, 1.0, v21
	v_rcp_f32_e32 v21, v21
	v_mul_f32_e32 v22, v22, v23
	v_mul_f32_e32 v23, v97, v29
	v_exp_f32_e64 v28, -v98
	v_mul_f32_e32 v21, v21, v23
	v_exp_f32_e64 v23, -v99
	v_cvt_pk_bf16_f32 v38, v22, v21
	v_add_f32_e32 v21, 1.0, v28
	v_rcp_f32_e32 v21, v21
	v_add_f32_e32 v22, 1.0, v23
	v_rcp_f32_e32 v22, v22
	v_mul_f32_e32 v23, v98, v30
	v_mul_f32_e32 v21, v21, v23
	v_mul_f32_e32 v23, v99, v31
	v_mul_f32_e32 v22, v22, v23
	v_cvt_pk_bf16_f32 v39, v21, v22
	v_or_b32_e32 v21, 2, v20
	v_mad_i64_i32 v[22:23], s[10:11], v21, s92, v[6:7]
	v_exp_f32_e64 v21, -v116
	v_lshl_add_u64 v[22:23], v[22:23], 0, v[4:5]
	global_store_dwordx4 v[22:23], v[36:39], off sc1
	v_exp_f32_e64 v22, -v117
	v_add_f32_e32 v21, 1.0, v21
	v_rcp_f32_e32 v21, v21
	v_mul_f32_e32 v23, v116, v52
	v_add_f32_e32 v22, 1.0, v22
	v_rcp_f32_e32 v22, v22
	v_mul_f32_e32 v21, v21, v23
	v_mul_f32_e32 v23, v117, v53
	v_exp_f32_e64 v28, -v118
	v_mul_f32_e32 v22, v22, v23
	v_cvt_pk_bf16_f32 v22, v21, v22
	v_exp_f32_e64 v21, -v119
	v_add_f32_e32 v23, 1.0, v28
	v_rcp_f32_e32 v23, v23
	v_mul_f32_e32 v28, v118, v54
	v_add_f32_e32 v21, 1.0, v21
	v_rcp_f32_e32 v21, v21
	v_mul_f32_e32 v23, v23, v28
	v_mul_f32_e32 v28, v119, v55
	v_exp_f32_e64 v29, -v92
	v_mul_f32_e32 v21, v21, v28
	v_cvt_pk_bf16_f32 v23, v23, v21
	v_exp_f32_e64 v21, -v93
	v_add_f32_e32 v28, 1.0, v29
	v_rcp_f32_e32 v28, v28
	v_mul_f32_e32 v25, v93, v25
	v_add_f32_e32 v21, 1.0, v21
	v_rcp_f32_e32 v21, v21
	v_mul_f32_e32 v24, v28, v24
	v_exp_f32_e64 v28, -v94
	v_mul_f32_e32 v26, v94, v26
	v_mul_f32_e32 v21, v21, v25
	v_exp_f32_e64 v25, -v95
	v_cvt_pk_bf16_f32 v24, v24, v21
	v_add_f32_e32 v21, 1.0, v28
	v_rcp_f32_e32 v21, v21
	v_add_f32_e32 v25, 1.0, v25
	v_rcp_f32_e32 v25, v25
	v_mul_f32_e32 v17, v89, v17
	v_mul_f32_e32 v21, v21, v26
	v_mul_f32_e32 v26, v95, v27
	v_mul_f32_e32 v25, v25, v26
	v_cvt_pk_bf16_f32 v25, v21, v25
	v_or_b32_e32 v21, 3, v20
	v_mad_i64_i32 v[26:27], s[10:11], v21, s92, v[6:7]
	v_exp_f32_e64 v21, -v112
	v_lshl_add_u64 v[26:27], v[26:27], 0, v[4:5]
	global_store_dwordx4 v[26:27], v[22:25], off sc1
	v_mul_f32_e32 v16, v88, v16
	v_add_f32_e32 v21, 1.0, v21
	v_exp_f32_e64 v22, -v113
	v_rcp_f32_e32 v21, v21
	v_mul_f32_e32 v23, v112, v48
	v_exp_f32_e64 v24, -v114
	v_add_f32_e32 v22, 1.0, v22
	v_rcp_f32_e32 v22, v22
	v_mul_f32_e32 v21, v21, v23
	v_mul_f32_e32 v23, v113, v49
	v_exp_f32_e64 v25, -v88
	v_mul_f32_e32 v22, v22, v23
	v_cvt_pk_bf16_f32 v22, v21, v22
	v_exp_f32_e64 v21, -v115
	v_add_f32_e32 v23, 1.0, v24
	v_rcp_f32_e32 v23, v23
	v_mul_f32_e32 v24, v114, v50
	v_add_f32_e32 v21, 1.0, v21
	v_rcp_f32_e32 v21, v21
	v_mul_f32_e32 v23, v23, v24
	v_mul_f32_e32 v24, v115, v51
	v_mul_f32_e32 v18, v90, v18
; __device__ __forceinline__ unsigned cvt_pk_bf16(float lo, float hi) { unsigned r; asm volatile("v_cvt_pk_bf16_f32 %0, %1, %2" : "=v"(r) : "v"(lo), "v"(hi)); return r; }
; #define SG2(gx, vx) (((gx) * (vx)) * __builtin_amdgcn_rcpf(1.0f + __builtin_amdgcn_exp2f(-(gx))))
;     __device__ __forceinline__ void operator()(f32x4 (&acc)[2][2][4][2], const Unit& u, int wr, int wc, int fr, int fq) const {
;     ...
;             for (int m = 0; m < 4; ++m) {
;                 const f32x4 g0 = acc[ai][0][m][0], g1 = acc[ai][0][m][1], v0 = acc[ai][1][m][0], v1 = acc[ai][1][m][1];
;     ...
;                 u32x4 w; w.x = cvt_pk_bf16(SG2(g0[0], v0[0]), SG2(g0[1], v0[1])); w.y = cvt_pk_bf16(SG2(g0[2], v0[2]), SG2(g0[3], v0[3]));
;                 w.z = cvt_pk_bf16(SG2(g1[0], v1[0]), SG2(g1[1], v1[1])); w.w = cvt_pk_bf16(SG2(g1[2], v1[2]), SG2(g1[3], v1[3]));
;     ...
;                 const bool valid = !((ai == 0 && m == 0 && f0) || (ai == 1 && m == 3 && f15));
;                 if (valid) *(u32x4*)(A + (size_t)(sc * 128 + ai * 64 + 4 * fr + m) * DFF + J0) = w;
	v_mul_f32_e32 v21, v21, v24
	v_cvt_pk_bf16_f32 v23, v23, v21
	v_exp_f32_e64 v21, -v89
	v_add_f32_e32 v24, 1.0, v25
	v_rcp_f32_e32 v24, v24
	v_exp_f32_e64 v25, -v90
	v_add_f32_e32 v21, 1.0, v21
	v_rcp_f32_e32 v21, v21
	v_mul_f32_e32 v16, v24, v16
	v_mul_f32_e32 v12, v76, v12
	v_mul_f32_e32 v13, v77, v13
	v_mul_f32_e32 v17, v21, v17
	v_exp_f32_e64 v21, -v91
	v_cvt_pk_bf16_f32 v24, v16, v17
	v_add_f32_e32 v16, 1.0, v25
	v_rcp_f32_e32 v16, v16
	v_add_f32_e32 v17, 1.0, v21
	v_rcp_f32_e32 v17, v17
	v_exp_f32_e64 v21, -v76
	v_mul_f32_e32 v16, v16, v18
	v_mul_f32_e32 v18, v91, v19
	v_mul_f32_e32 v17, v17, v18
	v_cvt_pk_bf16_f32 v25, v16, v17
	v_or_b32_e32 v16, 64, v20
	v_mad_i64_i32 v[16:17], s[10:11], v16, s92, v[6:7]
	v_exp_f32_e64 v18, -v104
	v_lshl_add_u64 v[16:17], v[16:17], 0, v[4:5]
	global_store_dwordx4 v[16:17], v[22:25], off sc1
	v_exp_f32_e64 v16, -v105
	v_add_f32_e32 v17, 1.0, v18
	v_rcp_f32_e32 v17, v17
	v_mul_f32_e32 v18, v104, v44
	v_add_f32_e32 v16, 1.0, v16
	v_rcp_f32_e32 v16, v16
	v_mul_f32_e32 v17, v17, v18
	v_mul_f32_e32 v18, v105, v45
	v_exp_f32_e64 v19, -v106
	v_mul_f32_e32 v16, v16, v18
	v_cvt_pk_bf16_f32 v16, v17, v16
	v_exp_f32_e64 v17, -v107
	v_add_f32_e32 v18, 1.0, v19
	v_rcp_f32_e32 v18, v18
	v_mul_f32_e32 v19, v106, v46
	v_add_f32_e32 v17, 1.0, v17
	v_rcp_f32_e32 v17, v17
	v_mul_f32_e32 v18, v18, v19
	v_mul_f32_e32 v19, v107, v47
	v_mul_f32_e32 v14, v78, v14
	v_mul_f32_e32 v17, v17, v19
	v_cvt_pk_bf16_f32 v17, v18, v17
	v_exp_f32_e64 v18, -v77
	v_add_f32_e32 v19, 1.0, v21
	v_rcp_f32_e32 v19, v19
	v_exp_f32_e64 v21, -v79
	v_add_f32_e32 v18, 1.0, v18
	v_rcp_f32_e32 v18, v18
	v_mul_f32_e32 v12, v19, v12
	v_exp_f32_e64 v19, -v78
	v_mul_f32_e32 v8, v72, v8
	v_mul_f32_e32 v13, v18, v13
	v_cvt_pk_bf16_f32 v18, v12, v13
	v_add_f32_e32 v12, 1.0, v19
	v_rcp_f32_e32 v12, v12
	v_add_f32_e32 v13, 1.0, v21
	v_rcp_f32_e32 v13, v13
	v_mul_f32_e32 v9, v73, v9
	v_mul_f32_e32 v12, v12, v14
	v_mul_f32_e32 v14, v79, v15
	v_mul_f32_e32 v13, v13, v14
	v_cvt_pk_bf16_f32 v19, v12, v13
	v_or_b32_e32 v12, 0x41, v20
	v_mad_i64_i32 v[12:13], s[10:11], v12, s92, v[6:7]
	v_exp_f32_e64 v14, -v100
	v_lshl_add_u64 v[12:13], v[12:13], 0, v[4:5]
	global_store_dwordx4 v[12:13], v[16:19], off sc1
	v_exp_f32_e64 v12, -v101
	v_add_f32_e32 v13, 1.0, v14
	v_rcp_f32_e32 v13, v13
	v_mul_f32_e32 v14, v100, v40
	v_add_f32_e32 v12, 1.0, v12
	v_rcp_f32_e32 v12, v12
	v_mul_f32_e32 v13, v13, v14
	v_mul_f32_e32 v14, v101, v41
	v_exp_f32_e64 v15, -v102
	v_mul_f32_e32 v12, v12, v14
	v_cvt_pk_bf16_f32 v12, v13, v12
	v_exp_f32_e64 v13, -v103
	v_add_f32_e32 v14, 1.0, v15
	v_rcp_f32_e32 v14, v14
	v_exp_f32_e64 v16, -v72
	v_add_f32_e32 v13, 1.0, v13
	v_rcp_f32_e32 v13, v13
	v_mul_f32_e32 v15, v102, v42
	v_mul_f32_e32 v14, v14, v15
	v_mul_f32_e32 v15, v103, v43
	v_mul_f32_e32 v13, v13, v15
	v_cvt_pk_bf16_f32 v13, v14, v13
	v_exp_f32_e64 v14, -v73
	v_add_f32_e32 v15, 1.0, v16
	v_rcp_f32_e32 v15, v15
	v_exp_f32_e64 v16, -v75
	v_add_f32_e32 v14, 1.0, v14
	v_rcp_f32_e32 v14, v14
	v_mul_f32_e32 v8, v15, v8
	v_exp_f32_e64 v15, -v74
	v_mul_f32_e32 v10, v74, v10
	v_mul_f32_e32 v9, v14, v9
	v_cvt_pk_bf16_f32 v14, v8, v9
	v_add_f32_e32 v8, 1.0, v15
	v_rcp_f32_e32 v8, v8
	v_add_f32_e32 v9, 1.0, v16
	v_rcp_f32_e32 v9, v9
	v_mul_f32_e32 v0, v64, v0
	v_mul_f32_e32 v8, v8, v10
	v_mul_f32_e32 v10, v75, v11
	v_mul_f32_e32 v9, v9, v10
	v_cvt_pk_bf16_f32 v15, v8, v9
	v_or_b32_e32 v8, 0x42, v20
	v_mad_i64_i32 v[6:7], s[10:11], v8, s92, v[6:7]
	v_exp_f32_e64 v8, -v84
	v_lshl_add_u64 v[4:5], v[6:7], 0, v[4:5]
	global_store_dwordx4 v[4:5], v[12:15], off sc1
	v_exp_f32_e64 v4, -v85
	v_add_f32_e32 v5, 1.0, v8
	v_rcp_f32_e32 v5, v5
	v_mul_f32_e32 v6, v84, v32
	v_add_f32_e32 v4, 1.0, v4
	v_rcp_f32_e32 v4, v4
	v_mul_f32_e32 v5, v5, v6
	v_mul_f32_e32 v6, v85, v33
	v_exp_f32_e64 v7, -v86
	v_mul_f32_e32 v4, v4, v6
	v_cvt_pk_bf16_f32 v4, v5, v4
	v_exp_f32_e64 v5, -v87
	v_add_f32_e32 v6, 1.0, v7
	v_rcp_f32_e32 v6, v6
	v_exp_f32_e64 v8, -v64
	v_add_f32_e32 v5, 1.0, v5
	v_rcp_f32_e32 v5, v5
	v_mul_f32_e32 v7, v86, v34
	v_mul_f32_e32 v6, v6, v7
	v_mul_f32_e32 v7, v87, v35
	v_mul_f32_e32 v5, v5, v7
	v_cvt_pk_bf16_f32 v5, v6, v5
	v_exp_f32_e64 v6, -v65
	v_add_f32_e32 v7, 1.0, v8
	v_rcp_f32_e32 v7, v7
	v_exp_f32_e64 v8, -v67
	v_add_f32_e32 v6, 1.0, v6
	v_rcp_f32_e32 v6, v6
	v_mul_f32_e32 v0, v7, v0
	v_exp_f32_e64 v7, -v66
	v_mul_f32_e32 v1, v65, v1
	v_mul_f32_e32 v1, v6, v1
	v_cvt_pk_bf16_f32 v6, v0, v1
	v_add_f32_e32 v0, 1.0, v7
	v_rcp_f32_e32 v0, v0
	v_add_f32_e32 v1, 1.0, v8
	v_rcp_f32_e32 v1, v1
	v_mul_f32_e32 v2, v66, v2
	v_mul_f32_e32 v0, v0, v2
	v_mul_f32_e32 v2, v67, v3
	v_mul_f32_e32 v1, v1, v2
	v_cvt_pk_bf16_f32 v7, v0, v1
	s_and_saveexec_b64 s[12:13], s[6:7]
	s_cbranch_execz .LBB0_796
	v_or_b32_e32 v2, 0x43, v20
	v_mov_b64_e32 v[0:1], s[18:19]
	v_mad_i64_i32 v[0:1], s[10:11], v2, s92, v[0:1]
	v_lshl_add_u64 v[0:1], v[148:149], 1, v[0:1]
	global_store_dwordx4 v[0:1], v[4:7], off sc1
	s_branch .LBB0_796
